# stack + weight warm-up prefetches for every GEMM phase (next-layer in-GEMM, Wo during attention, gates/wo/glu weights during conv/scans, w_ple)
# baseline (speedup 1.0000x reference)
; __device__ __forceinline__ int launder(int v) { asm volatile("" : "+v"(v)); return v; }
; __device__ __forceinline__ void conv_phase(const bf16_t* XB, const float* cw, const float* cb, bf16_t* XC, int bid, int G) {
;     const int gtid = bid * NTHR + launder(threadIdx.x), nthreads = G * NTHR;
;     for (int item = gtid; item < 512 * 512; item += nthreads) {
;         const int c = (item & 511) * 4, t0 = (item >> 9) * 16;
;         const f32x4 w0 = *(const f32x4*)(cw + c), w1 = *(const f32x4*)(cw + D + c), w2 = *(const f32x4*)(cw + 2 * D + c), w3 = *(const f32x4*)(cw + 3 * D + c), bb = *(const f32x4*)(cb + c);
.LBB0_603:
	s_or_b64 exec, exec, s[4:5]
	v_readlane_b32 s0, v255, 39
	s_lshl_b32 s0, s0, 3
	s_add_u32 s8, s76, s0
	s_waitcnt lgkmcnt(0)
	v_mov_b32_e32 v2, v246
	v_readlane_b32 s0, v254, 4
	s_barrier
	s_addc_u32 s9, s77, 0
	s_cmp_ge_u32 s74, 32
	s_cbranch_scc1 .Lwpf_h
	s_lshl_b32 s100, s74, 9
	v_add_u32_e32 v60, s100, v246
	v_lshrrev_b32_e32 v61, 2, v60
	v_and_b32_e32 v60, 3, v60
	v_lshlrev_b32_e32 v60, 7, v60
	v_lshl_add_u32 v60, v61, 9, v60
	s_add_u32 s100, s38, 0x14700000
	s_addc_u32 s101, s39, 0
	s_mov_b32 m0, 0x21000
	s_nop 0
	global_load_lds_dword v60, s[100:101]
.Lwpf_h:
	v_add_u32_e32 v1, s0, v2
	s_mov_b32 s0, 0x40000
	v_cmp_gt_i32_e32 vcc, s0, v1
	s_and_saveexec_b64 s[12:13], vcc
	s_cbranch_execz .LBB0_612
	s_load_dwordx4 s[4:7], s[8:9], 0x10
	v_readlane_b32 s0, v254, 61
	s_mov_b64 s[22:23], 0
	s_waitcnt lgkmcnt(0)
	s_add_u32 s16, s4, 0x2000
	s_addc_u32 s17, s5, 0
	s_add_u32 s18, s4, 0x4000
	s_addc_u32 s19, s5, 0
	s_add_u32 s20, s4, 0x6000
	v_lshl_add_u32 v52, v2, 2, s0
	s_addc_u32 s21, s5, 0
	s_branch .LBB0_606

; __device__ __forceinline__ int launder(int v) { asm volatile("" : "+v"(v)); return v; }
; __device__ __forceinline__ float lru_sp(float lam) { const float x = -lam; return -8.0f * ((x > 0.f ? x : 0.f) + log1pf(__expf(-fabsf(x)))); }
; __device__ __forceinline__ void lru_scan1(const bf16_t* Ab, const bf16_t* Bb, const bf16_t* XC, const float* lam, float* PE, int bid, int G) {
;     const int gtid = bid * NTHR + launder(threadIdx.x), nthreads = G * NTHR;
;     for (int item = gtid; item < LRU_NC * D; item += nthreads) {
;         const int ch = item & (D - 1), c = item >> 11;
;         const float sp = lru_sp(lam[ch]);
.LBB0_740:
	s_or_b64 exec, exec, s[4:5]
	s_waitcnt lgkmcnt(0)
	s_barrier
	s_load_dwordx2 s[4:5], s[8:9], 0x40
	s_cmp_ge_u32 s74, 16
	s_cbranch_scc1 .Lwpf_i
	s_lshl_b32 s100, s74, 9
	v_add_u32_e32 v130, s100, v246
	v_lshrrev_b32_e32 v131, 2, v130
	v_and_b32_e32 v130, 3, v130
	v_lshlrev_b32_e32 v130, 7, v130
	v_lshl_add_u32 v130, v131, 12, v130
	s_add_u32 s100, s38, 0x14900000
	s_addc_u32 s101, s39, 0
	s_mov_b32 m0, 0x21000
	s_nop 0
	global_load_lds_dword v130, s[100:101]
.Lwpf_i:
	v_mov_b32_e32 v1, v246
	v_readlane_b32 s0, v254, 4
	s_nop 1
	v_add_u32_e32 v1, s0, v1
	s_mov_b32 s0, 0x20000
	v_cmp_gt_i32_e32 vcc, s0, v1
	s_and_saveexec_b64 s[6:7], vcc
	s_cbranch_execz .LBB0_810
	s_mov_b64 s[8:9], 0
	s_branch .LBB0_743

; #define LAS __attribute__((address_space(3)))
; __device__ __forceinline__ int launder(int v) { asm volatile("" : "+v"(v)); return v; }
; __device__ __forceinline__ void s5_scan1(LAS unsigned char* lds, const S5Params& P, const bf16_t* U, float* ES, int bid, int G) {
;     const int tid = launder(threadIdx.x), lane = tid & 63, wave = __builtin_amdgcn_readfirstlane(tid >> 6), gw = bid * NWAVES + wave, ngw = G * NWAVES;
;     LAS unsigned char* wlds = lds + wave * S5_WAVE_LDS;
;     for (int item = gw; item < 128 * S5_NC; item += ngw) {
;         const int g = item & 127, c = item >> 7;
;         S5Item L; s5_item_setup(P, g, lane, wlds, L);
.LBB0_1168:
	s_or_b64 exec, exec, s[4:5]
	s_waitcnt lgkmcnt(0)
	v_mov_b32_e32 v2, v246
	s_barrier
	s_cmp_ge_u32 s74, 16
	s_cbranch_scc1 .Lwpf_j
	s_lshl_b32 s100, s74, 9
	v_add_u32_e32 v100, s100, v246
	v_lshrrev_b32_e32 v101, 2, v100
	v_and_b32_e32 v100, 3, v100
	v_lshlrev_b32_e32 v100, 7, v100
	v_lshl_add_u32 v100, v101, 12, v100
	s_add_u32 s100, s38, 0x15900000
	s_addc_u32 s101, s39, 0
	s_mov_b32 m0, 0x21000
	s_nop 0
	global_load_lds_dword v100, s[100:101]
.Lwpf_j:
	s_nop 0
	v_readfirstlane_b32 s0, v2
	s_ashr_i32 s0, s0, 6
	s_add_i32 s44, s0, s75
	s_cmpk_gt_i32 s44, 0xfff
	s_cbranch_scc1 .LBB0_1181
	v_and_b32_e32 v3, 14, v2
	v_and_b32_e32 v4, 1, v2
	v_cmp_eq_u32_e64 s[6:7], 0, v4
	v_or_b32_e32 v4, 16, v3
	v_lshrrev_b32_e32 v80, 1, v4
	v_or_b32_e32 v4, 32, v3
	v_lshrrev_b32_e32 v81, 1, v4
	v_or_b32_e32 v4, 48, v3
	s_mulk_i32 s0, 0x3800
	v_lshrrev_b32_e32 v82, 1, v4
	v_or_b32_e32 v4, 64, v3
	s_add_i32 s45, s0, 0
	v_lshrrev_b32_e32 v83, 1, v4
	v_or_b32_e32 v4, 0x50, v3
	v_lshl_add_u32 v79, v3, 2, s45
	v_lshrrev_b32_e32 v84, 1, v4
	v_or_b32_e32 v4, 0x60, v3
	v_or_b32_e32 v3, 0x70, v3
	v_lshrrev_b32_e32 v86, 1, v3
	v_lshlrev_b32_e32 v3, 2, v2
	v_lshrrev_b32_e32 v85, 1, v4
	v_and_b32_e32 v4, 12, v3
	v_lshlrev_b32_e32 v6, 1, v4
	v_mov_b32_e32 v7, v0
	v_lshlrev_b32_e32 v3, 4, v2
	v_lshl_add_u64 v[52:53], s[58:59], 0, v[6:7]
	v_and_b32_e32 v3, 0x3c0, v3
	v_lshlrev_b32_e32 v6, 2, v4
	v_mov_b32_e32 v5, s45
	v_add3_u32 v89, s45, v3, v6
	v_and_b32_e32 v3, 15, v2
	v_lshlrev_b32_e32 v6, 1, v2
	s_movk_i32 s0, 0x210
	v_and_b32_e32 v1, 63, v2
	v_lshlrev_b32_e32 v7, 6, v3
	v_and_b32_e32 v6, 32, v6
	v_mad_u32_u24 v3, v3, s0, v5
	v_readlane_b32 s0, v254, 17
	v_lshlrev_b32_e32 v50, 3, v1
	v_bfe_u32 v78, v2, 1, 3
	v_bfe_u32 v87, v2, 2, 4
	v_add3_u32 v90, s45, v7, v6
	v_and_b32_e32 v2, 48, v2
	v_mov_b32_e32 v51, v0
	v_readlane_b32 s1, v254, 18
	v_mov_b32_e32 v7, v0
	v_cmp_lt_u32_e64 s[4:5], 31, v1
	v_or_b32_e32 v88, 64, v87
	v_lshl_add_u64 v[54:55], s[0:1], 0, v[50:51]
	v_lshl_add_u64 v[56:57], s[22:23], 0, v[6:7]
	v_lshl_add_u64 v[58:59], s[24:25], 0, v[6:7]
	v_lshlrev_b32_e32 v60, 1, v4
	v_add_u32_e32 v51, v3, v2

; __device__ __forceinline__ int launder(int v) { asm volatile("" : "+v"(v)); return v; }
; __device__ __forceinline__ void attn_phase(LAS unsigned char* lds, const bf16_t* QKV, const int* positions, const float* qn, const float* kn, const float* sinks, bf16_t* AO, int G, int bid) {
;     const int tid = launder(threadIdx.x), lane = tid & 63, wave = __builtin_amdgcn_readfirstlane(tid >> 6);
;     const int fr = lane & 15, fq = lane >> 4;
;     for (int unit = bid; unit < (T / 128) * 4; unit += G) {
;         const int nb = unit >> 2, hk = unit & 3;
;         {
;             const int kk = tid >> 1, half = tid & 1; const int tok = (nb - 1) * 128 + kk;
;             u32x4 kraw[4], vraw[4];
;             if (tok >= 0) {
;                 const u32x4* kp = (const u32x4*)(QKV + (size_t)tok * NQKV + 2048 + hk * 64 + half * 32);
;                 const u32x4* vp = (const u32x4*)(QKV + (size_t)tok * NQKV + 2304 + hk * 64 + half * 32);
.LBB0_1858:
	s_or_b64 exec, exec, s[4:5]
	v_readlane_b32 s0, v254, 52
	v_mov_b32_e32 v1, v246
	v_readlane_b32 s1, v254, 53
	s_waitcnt lgkmcnt(0)
	s_barrier
	s_cmp_ge_u32 s74, 16
	s_cbranch_scc1 .Lwpf_g
	s_lshl_b32 s100, s74, 9
	v_add_u32_e32 v212, s100, v246
	v_lshrrev_b32_e32 v213, 2, v212
	v_and_b32_e32 v212, 3, v212
	v_lshlrev_b32_e32 v212, 7, v212
	v_lshl_add_u32 v212, v213, 12, v212
	v_readlane_b32 s100, v255, 42
	s_nop 3
	s_mov_b32 s101, 0x17300000
	s_cmp_eq_u32 s100, 0
	s_cselect_b32 s101, 0x12f00000, s101
	s_add_u32 s100, s38, s101
	s_addc_u32 s101, s39, 0
	s_mov_b32 m0, 0x21000
	s_nop 0
	global_load_lds_dword v212, s[100:101]
.Lwpf_g:
	s_andn2_b64 vcc, exec, s[0:1]
	v_readfirstlane_b32 s0, v1
	s_cbranch_vccnz .LBB0_1964
	v_readlane_b32 s1, v255, 39
	s_lshl_b32 s1, s1, 3
	s_load_dwordx4 s[8:11], s[76:77], s1 offset:0x10
	s_load_dwordx2 s[16:17], s[76:77], s1 offset:0x20
	s_ashr_i32 s14, s0, 6
	v_ashrrev_i32_e32 v4, 1, v1
	s_movk_i32 s0, 0x90
	v_and_b32_e32 v3, 63, v1
	v_and_b32_e32 v10, 1, v1
	v_mul_lo_u32 v5, v4, s0
	v_readlane_b32 s0, v255, 11
	v_lshlrev_b32_e32 v2, 5, v10
	v_lshlrev_b32_e32 v3, 2, v3
	v_lshl_add_u32 v116, v4, 2, s0
	s_movk_i32 s0, 0x4200
	v_and_b32_e32 v112, 15, v1
	v_bfe_u32 v7, v1, 4, 2
	v_xor_b32_e32 v114, 4, v3
	v_and_b32_e32 v115, -2, v1
	v_xor_b32_e32 v117, 64, v3
	v_xor_b32_e32 v118, 0x80, v3
	v_and_b32_e32 v6, 48, v1
	v_lshlrev_b32_e32 v8, 7, v10
	v_mov_b32_e32 v9, v0
	v_or_b32_e32 v1, 2, v2
	v_mad_u32_u24 v3, v10, s0, 0
	s_movk_i32 s0, 0x210
	v_add_u32_e32 v113, 0xffffff80, v4
	v_add_u32_e32 v11, 0, v5
	v_lshlrev_b32_e32 v4, 3, v7
	v_mov_b32_e32 v5, v0
	s_waitcnt lgkmcnt(0)
	v_lshl_add_u64 v[94:95], s[10:11], 0, v[8:9]
	v_mad_u32_u24 v120, v1, s0, 0
	v_lshlrev_b32_e32 v8, 5, v7
	v_mul_u32_u24_e32 v7, 0x210, v112
	v_lshlrev_b32_e32 v12, 6, v10
	v_cmp_eq_u32_e64 s[4:5], 0, v10
	v_add_u32_e32 v119, 0, v6
	v_lshl_add_u64 v[92:93], s[66:67], 0, v[4:5]
	v_add_u32_e32 v1, 0x420, v120
	v_add_u32_e32 v5, 0x840, v120
	v_add_u32_e32 v10, 0xc60, v120
	v_add_u32_e32 v13, 0x1080, v120
	v_add_u32_e32 v14, 0x14a0, v120
	v_add_u32_e32 v15, 0x18c0, v120
	v_add_u32_e32 v16, 0x1ce0, v120
	v_add_u32_e32 v17, 0x2100, v120
	v_add_u32_e32 v18, 0x2520, v120
	v_add_u32_e32 v19, 0x2940, v120
	v_add_u32_e32 v20, 0x2d60, v120
	v_add_u32_e32 v21, 0x3180, v120
	v_add_u32_e32 v22, 0x35a0, v120
	v_add_u32_e32 v23, 0x39c0, v120
	v_lshl_add_u64 v[96:97], s[8:9], 0, v[8:9]
	v_mul_u32_u24_e32 v8, 0x90, v112
	v_add3_u32 v121, 0, v4, v7
	v_mov_b32_e32 v7, v0
	v_lshl_add_u64 v[98:99], s[58:59], 0, v[6:7]
	v_lshlrev_b32_e32 v100, 1, v2
	v_add_u32_e32 v122, v11, v12
	v_add_u32_e32 v123, v3, v115
	v_add_u32_e32 v124, v1, v115
	v_add_u32_e32 v125, v5, v115
	v_add_u32_e32 v126, v10, v115
	v_add_u32_e32 v127, v13, v115
	v_add_u32_e32 v128, v14, v115
	v_add_u32_e32 v129, v15, v115
	v_add_u32_e32 v130, v16, v115
	v_add_u32_e32 v131, v17, v115
	v_add_u32_e32 v132, v18, v115
	v_add_u32_e32 v133, v19, v115
	v_add_u32_e32 v134, v20, v115
	v_add_u32_e32 v135, v21, v115
	v_add_u32_e32 v136, v22, v115
	v_add_u32_e32 v137, v23, v115
	v_lshlrev_b32_e32 v102, 1, v4
	v_add_u32_e32 v138, v119, v8
	s_mov_b32 s18, s74
	s_cmp_lg_u32 s78, 0x100
	s_cbranch_scc1 .Lattn_noperm
	s_and_b32 s18, s74, 7
	s_lshl_b32 s18, s18, 5
	s_lshr_b32 s15, s74, 3
	s_or_b32 s18, s18, s15

;     __device__ void init(int M, int N, int G_, int c_) { nM = M / BM; nN = N / BM; nwg = nM * nN; G = launder_s(G_); c = launder_s(c_); }
; __global__ void __launch_bounds__(NTHR, 2) mk_fwd(Args args) {
;     ...
;             { pg8::Gemm g{HB0, (const bf16_t*)(wl + WOFF_UP), T, DFF, D, D, D, 0, 0}; pg8::StaticOrder S; S.init(T, DFF, G, bid); pg8::EpiBf16<2> E{UP, DFF, nullptr}; pg8::gemm_phase(lds, g, S, E); }
;             if (l != 3) { pg8::Gemm g{PBF + (size_t)l * T * PLE, (const bf16_t*)(wl + WOFF_PLE), T, D, PLE, PLE, PLE, 0, 0}; pg8::StaticOrder S; S.init(T, D, G, bid); pg8::EpiBf16<0> E{PP, D, nullptr}; pg8::gemm_phase(lds, g, S, E); }
.Lwpf_d:
	s_cmp_ge_u32 s74, 16
	s_cbranch_scc1 .Lwpf_D
	s_lshl_b32 s100, s74, 9
	v_add_u32_e32 v146, s100, v246
	v_lshrrev_b32_e32 v147, 2, v146
	v_and_b32_e32 v146, 3, v146
	v_lshlrev_b32_e32 v146, 7, v146
	v_lshl_add_u32 v146, v147, 9, v146
	s_add_u32 s100, s88, 0x4800000
	s_addc_u32 s101, s89, 0
	s_mov_b32 m0, 0x21000
	s_nop 0
	global_load_lds_dword v146, s[100:101]

; #define PG8_STAGE(bufoff, gbase, voff) do { _Pragma("unroll") for (int _i = 0; _i < 2; ++_i) \
;         __builtin_amdgcn_global_load_lds((const unsigned*)((const char*)(gbase) + (voff)[_i]), (LAS unsigned*)(lds + (bufoff) + ldsw + _i * 8192), 16, 0, 0); } while (0)
; #define PG8_LDA(dst, b, h) do { _Pragma("unroll") for (int m = 0; m < 4; ++m) _Pragma("unroll") for (int k = 0; k < 2; ++k) dst[m][k] = *(const LAS bf16x8*)(lds + PG8_SA(b, h) + aoff + m * 2048 + k * 1024); } while (0)
; #define PG8_LDB(dst, b, h) do { _Pragma("unroll") for (int n = 0; n < 2; ++n) _Pragma("unroll") for (int k = 0; k < 2; ++k) dst[n][k] = *(const LAS bf16x8*)(lds + PG8_SB(b, h) + boff + n * 2048 + k * 1024); } while (0)
; #define PG8_MMA(ai, bj, At, Bt) do { __builtin_amdgcn_s_setprio(1); _Pragma("unroll") for (int m = 0; m < 4; ++m) _Pragma("unroll") for (int n = 0; n < 2; ++n) _Pragma("unroll") for (int k = 0; k < 2; ++k) \
;         acc[ai][bj][m][n] = __builtin_amdgcn_mfma_f32_16x16x32_bf16(Bt[n][k], At[m][k], acc[ai][bj][m][n], 0, 0, 0); __builtin_amdgcn_s_setprio(0); } while (0)
; #define PG8_WAIT_V(n) asm volatile("s_waitcnt vmcnt(" #n ")" ::: "memory")
; #define PG8_WAIT_L(n) asm volatile("s_waitcnt lgkmcnt(" #n ")" ::: "memory")
; #define PG8_BAR __builtin_amdgcn_s_barrier()
; #define PG8_SCHED __builtin_amdgcn_sched_barrier(0)
; template <class Epi>
; __device__ __forceinline__ void gemm_phase(LAS unsigned char* lds, const Gemm g, const StaticOrder& S, const Epi& E) {
;     ...
;             const bool last = (t == nt - 2);
;             const char* a1 = cA + (size_t)(t + 1) * kstep;
;             const char* a2 = last ? nA : cA + (size_t)(t + 2) * kstep; const char* b2 = last ? nB : cB + (size_t)(t + 2) * kstep;
;             const char* a3 = a2 + kstep; const char* b3 = b2 + kstep;
;             PG8_LDB(B0, 0, 0); PG8_LDB(B1, 0, 1); PG8_SCHED; PG8_LDA(At, 0, 0); PG8_STAGE(PG8_SA(1, 1), a1 + hstepA, voffA);
;             PG8_WAIT_V(8); PG8_WAIT_L(0); PG8_BAR; PG8_MMA(0, 0, At, B0); PG8_MMA(0, 1, At, B1); PG8_BAR; PG8_SCHED;
;             PG8_LDA(At, 0, 1); PG8_STAGE(PG8_SB(0, 0), b2, voffB); PG8_STAGE(PG8_SB(0, 1), b2 + hstepB, voffB); PG8_STAGE(PG8_SA(0, 0), a2, voffA);
;             PG8_WAIT_V(8); PG8_WAIT_L(0); PG8_BAR; PG8_MMA(1, 0, At, B0); PG8_MMA(1, 1, At, B1); PG8_BAR; PG8_SCHED;
.LBB0_2332:
	s_add_u32 s14, s24, 0xfff80080
	s_addc_u32 s15, s25, -1
	s_add_i32 s41, 0, 0x10000
	s_cmp_eq_u32 s40, 28
	s_cselect_b32 s27, s1, s15
	s_cselect_b32 s26, s3, s14
	s_cselect_b32 s15, s9, s33
	s_cselect_b32 s14, s17, s19
	s_add_i32 s62, 0, 0x14000
	v_add_u32_e32 v142, s41, v1
	v_add_u32_e32 v170, s62, v1
	ds_read_b128 v[130:133], v142
	ds_read_b128 v[134:137], v142 offset:1024
	ds_read_b128 v[138:141], v142 offset:2048
	ds_read_b128 v[142:145], v142 offset:3072
	ds_read_b128 v[146:149], v170
	ds_read_b128 v[150:153], v170 offset:1024
	ds_read_b128 v[166:169], v170 offset:2048
	ds_read_b128 v[170:173], v170 offset:3072
	v_lshl_add_u64 v[178:179], s[24:25], 0, v[162:163]
	s_add_i32 m0, s35, 0xc000
	ds_read_b128 v[174:177], v181
	ds_read_b128 v[188:191], v181 offset:1024
	ds_read_b128 v[192:195], v181 offset:2048
	ds_read_b128 v[196:199], v181 offset:3072
	ds_read_b128 v[200:203], v181 offset:4096
	ds_read_b128 v[204:207], v181 offset:5120
	ds_read_b128 v[208:211], v181 offset:6144
	ds_read_b128 v[212:215], v181 offset:7168
	global_load_lds_dwordx4 v[178:179], off
	v_lshl_add_u64 v[178:179], s[24:25], 0, v[164:165]
	s_add_i32 m0, s35, 0xe000
	s_nop 0
	global_load_lds_dwordx4 v[178:179], off
	s_waitcnt vmcnt(8)
	s_waitcnt lgkmcnt(0)
	s_barrier
	s_setprio 1
	s_waitcnt lgkmcnt(0)
	v_mfma_f32_16x16x32_bf16 v[126:129], v[130:133], v[174:177], v[126:129]
	v_mfma_f32_16x16x32_bf16 v[122:125], v[138:141], v[174:177], v[122:125]
	v_mfma_f32_16x16x32_bf16 v[118:121], v[130:133], v[192:195], v[118:121]
	v_mfma_f32_16x16x32_bf16 v[114:117], v[138:141], v[192:195], v[114:117]
	v_mfma_f32_16x16x32_bf16 v[102:105], v[130:133], v[200:203], v[102:105]
	v_mfma_f32_16x16x32_bf16 v[98:101], v[138:141], v[200:203], v[98:101]
	v_mfma_f32_16x16x32_bf16 v[86:89], v[130:133], v[208:211], v[86:89]
	v_mfma_f32_16x16x32_bf16 v[82:85], v[138:141], v[208:211], v[82:85]
	v_mfma_f32_16x16x32_bf16 v[126:129], v[134:137], v[188:191], v[126:129]
	v_mfma_f32_16x16x32_bf16 v[122:125], v[142:145], v[188:191], v[122:125]
	v_mfma_f32_16x16x32_bf16 v[118:121], v[134:137], v[196:199], v[118:121]
	v_mfma_f32_16x16x32_bf16 v[114:117], v[142:145], v[196:199], v[114:117]
	v_mfma_f32_16x16x32_bf16 v[102:105], v[134:137], v[204:207], v[102:105]
	v_mfma_f32_16x16x32_bf16 v[98:101], v[142:145], v[204:207], v[98:101]
	v_mfma_f32_16x16x32_bf16 v[86:89], v[134:137], v[212:215], v[86:89]
	v_mfma_f32_16x16x32_bf16 v[82:85], v[142:145], v[212:215], v[82:85]
	s_setprio 0
	s_setprio 1
	v_mfma_f32_16x16x32_bf16 v[110:113], v[146:149], v[174:177], v[110:113]
	v_mfma_f32_16x16x32_bf16 v[106:109], v[166:169], v[174:177], v[106:109]
	v_mfma_f32_16x16x32_bf16 v[94:97], v[146:149], v[192:195], v[94:97]
	v_mfma_f32_16x16x32_bf16 v[90:93], v[166:169], v[192:195], v[90:93]
	v_mfma_f32_16x16x32_bf16 v[78:81], v[146:149], v[200:203], v[78:81]
	v_mfma_f32_16x16x32_bf16 v[74:77], v[166:169], v[200:203], v[74:77]
	v_mfma_f32_16x16x32_bf16 v[70:73], v[146:149], v[208:211], v[70:73]
	v_mfma_f32_16x16x32_bf16 v[66:69], v[166:169], v[208:211], v[66:69]
	v_mfma_f32_16x16x32_bf16 v[110:113], v[150:153], v[188:191], v[110:113]
	v_mfma_f32_16x16x32_bf16 v[106:109], v[170:173], v[188:191], v[106:109]
	v_mfma_f32_16x16x32_bf16 v[94:97], v[150:153], v[196:199], v[94:97]
	v_mfma_f32_16x16x32_bf16 v[90:93], v[170:173], v[196:199], v[90:93]
	v_mfma_f32_16x16x32_bf16 v[78:81], v[150:153], v[204:207], v[78:81]
	v_mfma_f32_16x16x32_bf16 v[74:77], v[170:173], v[204:207], v[74:77]
	v_mfma_f32_16x16x32_bf16 v[70:73], v[150:153], v[212:215], v[70:73]
	v_mfma_f32_16x16x32_bf16 v[66:69], v[170:173], v[212:215], v[66:69]
	s_setprio 0
	s_barrier
	s_add_i32 s41, s41, s34
	v_lshl_add_u64 v[178:179], s[14:15], 0, v[156:157]
	s_mov_b32 m0, s41
	ds_read_b128 v[174:177], v181 offset:16384
	ds_read_b128 v[188:191], v181 offset:17408
	ds_read_b128 v[192:195], v181 offset:18432
	ds_read_b128 v[196:199], v181 offset:19456
	ds_read_b128 v[200:203], v181 offset:20480
	ds_read_b128 v[204:207], v181 offset:21504
	ds_read_b128 v[208:211], v181 offset:22528
	ds_read_b128 v[212:215], v181 offset:23552
	global_load_lds_dwordx4 v[178:179], off
	s_add_i32 m0, s41, 0x2000
	s_add_u32 s52, s14, 0x80000
	v_lshl_add_u64 v[184:185], s[14:15], 0, v[160:161]
	s_addc_u32 s53, s15, 0
	s_add_i32 s41, s62, s34
	global_load_lds_dwordx4 v[184:185], off
	v_lshl_add_u64 v[216:217], s[52:53], 0, v[156:157]
	s_mov_b32 m0, s41
	v_lshl_add_u64 v[218:219], s[26:27], 0, v[158:159]
	global_load_lds_dwordx4 v[216:217], off
	v_lshl_add_u64 v[216:217], s[52:53], 0, v[160:161]
	s_add_i32 m0, s41, 0x2000
	s_nop 0
	global_load_lds_dwordx4 v[216:217], off
	v_lshl_add_u64 v[216:217], s[26:27], 0, v[154:155]
	s_mov_b32 m0, s35
	s_nop 0
	global_load_lds_dwordx4 v[216:217], off
	s_mov_b32 m0, s42
	s_nop 0
	global_load_lds_dwordx4 v[218:219], off
	s_waitcnt vmcnt(8)
	s_waitcnt lgkmcnt(0)
	s_barrier
; #define PG8_STAGE(bufoff, gbase, voff) do { _Pragma("unroll") for (int _i = 0; _i < 2; ++_i) \
;         __builtin_amdgcn_global_load_lds((const unsigned*)((const char*)(gbase) + (voff)[_i]), (LAS unsigned*)(lds + (bufoff) + ldsw + _i * 8192), 16, 0, 0); } while (0)
; #define PG8_LDA(dst, b, h) do { _Pragma("unroll") for (int m = 0; m < 4; ++m) _Pragma("unroll") for (int k = 0; k < 2; ++k) dst[m][k] = *(const LAS bf16x8*)(lds + PG8_SA(b, h) + aoff + m * 2048 + k * 1024); } while (0)
; #define PG8_LDB(dst, b, h) do { _Pragma("unroll") for (int n = 0; n < 2; ++n) _Pragma("unroll") for (int k = 0; k < 2; ++k) dst[n][k] = *(const LAS bf16x8*)(lds + PG8_SB(b, h) + boff + n * 2048 + k * 1024); } while (0)
; #define PG8_MMA(ai, bj, At, Bt) do { __builtin_amdgcn_s_setprio(1); _Pragma("unroll") for (int m = 0; m < 4; ++m) _Pragma("unroll") for (int n = 0; n < 2; ++n) _Pragma("unroll") for (int k = 0; k < 2; ++k) \
;         acc[ai][bj][m][n] = __builtin_amdgcn_mfma_f32_16x16x32_bf16(Bt[n][k], At[m][k], acc[ai][bj][m][n], 0, 0, 0); __builtin_amdgcn_s_setprio(0); } while (0)
; #define PG8_WAIT_V(n) asm volatile("s_waitcnt vmcnt(" #n ")" ::: "memory")
; #define PG8_WAIT_L(n) asm volatile("s_waitcnt lgkmcnt(" #n ")" ::: "memory")
; #define PG8_BAR __builtin_amdgcn_s_barrier()
; #define PG8_SCHED __builtin_amdgcn_sched_barrier(0)
; template <class Epi>
; __device__ __forceinline__ void gemm_phase(LAS unsigned char* lds, const Gemm g, const StaticOrder& S, const Epi& E) {
;     ...
;             PG8_WAIT_V(8); PG8_WAIT_L(0); PG8_BAR; PG8_MMA(1, 0, At, B0); PG8_MMA(1, 1, At, B1); PG8_BAR; PG8_SCHED;
;             PG8_LDB(B0, 1, 0); PG8_LDB(B1, 1, 1); PG8_SCHED; PG8_LDA(At, 1, 0); PG8_STAGE(PG8_SA(0, 1), a2 + hstepA, voffA);
;             PG8_WAIT_V(8); PG8_WAIT_L(0); PG8_BAR; PG8_MMA(0, 0, At, B0); PG8_MMA(0, 1, At, B1); PG8_BAR; PG8_SCHED;
;             PG8_LDA(At, 1, 1); PG8_STAGE(PG8_SB(1, 0), b3, voffB); PG8_STAGE(PG8_SB(1, 1), b3 + hstepB, voffB); PG8_STAGE(PG8_SA(1, 0), a3, voffA);
;             PG8_WAIT_V(8); PG8_WAIT_L(0); PG8_BAR; PG8_MMA(1, 0, At, B0); PG8_MMA(1, 1, At, B1); PG8_BAR; PG8_SCHED;
	s_setprio 1
	s_waitcnt lgkmcnt(0)
	v_mfma_f32_16x16x32_bf16 v[62:65], v[130:133], v[174:177], v[62:65]
	v_mfma_f32_16x16x32_bf16 v[58:61], v[138:141], v[174:177], v[58:61]
	v_mfma_f32_16x16x32_bf16 v[54:57], v[130:133], v[192:195], v[54:57]
	v_mfma_f32_16x16x32_bf16 v[50:53], v[138:141], v[192:195], v[50:53]
	v_mfma_f32_16x16x32_bf16 v[46:49], v[130:133], v[200:203], v[46:49]
	v_mfma_f32_16x16x32_bf16 v[38:41], v[138:141], v[200:203], v[38:41]
	v_mfma_f32_16x16x32_bf16 v[30:33], v[130:133], v[208:211], v[30:33]
	v_mfma_f32_16x16x32_bf16 v[22:25], v[138:141], v[208:211], v[22:25]
	v_mfma_f32_16x16x32_bf16 v[62:65], v[134:137], v[188:191], v[62:65]
	v_mfma_f32_16x16x32_bf16 v[58:61], v[142:145], v[188:191], v[58:61]
	v_mfma_f32_16x16x32_bf16 v[54:57], v[134:137], v[196:199], v[54:57]
	v_mfma_f32_16x16x32_bf16 v[50:53], v[142:145], v[196:199], v[50:53]
	v_mfma_f32_16x16x32_bf16 v[46:49], v[134:137], v[204:207], v[46:49]
	v_mfma_f32_16x16x32_bf16 v[38:41], v[142:145], v[204:207], v[38:41]
	v_mfma_f32_16x16x32_bf16 v[30:33], v[134:137], v[212:215], v[30:33]
	v_mfma_f32_16x16x32_bf16 v[22:25], v[142:145], v[212:215], v[22:25]
	s_setprio 0
	s_setprio 1
	v_mfma_f32_16x16x32_bf16 v[42:45], v[146:149], v[174:177], v[42:45]
	v_mfma_f32_16x16x32_bf16 v[34:37], v[166:169], v[174:177], v[34:37]
	v_mfma_f32_16x16x32_bf16 v[26:29], v[146:149], v[192:195], v[26:29]
	v_mfma_f32_16x16x32_bf16 v[18:21], v[166:169], v[192:195], v[18:21]
	v_mfma_f32_16x16x32_bf16 v[14:17], v[146:149], v[200:203], v[14:17]
	v_mfma_f32_16x16x32_bf16 v[10:13], v[166:169], v[200:203], v[10:13]
	v_mfma_f32_16x16x32_bf16 v[6:9], v[146:149], v[208:211], v[6:9]
	v_mfma_f32_16x16x32_bf16 v[2:5], v[166:169], v[208:211], v[2:5]
	v_mfma_f32_16x16x32_bf16 v[42:45], v[150:153], v[188:191], v[42:45]
	v_mfma_f32_16x16x32_bf16 v[34:37], v[170:173], v[188:191], v[34:37]
	v_mfma_f32_16x16x32_bf16 v[26:29], v[150:153], v[196:199], v[26:29]
	v_mfma_f32_16x16x32_bf16 v[18:21], v[170:173], v[196:199], v[18:21]
	v_mfma_f32_16x16x32_bf16 v[14:17], v[150:153], v[204:207], v[14:17]
	v_mfma_f32_16x16x32_bf16 v[10:13], v[170:173], v[204:207], v[10:13]
	v_mfma_f32_16x16x32_bf16 v[6:9], v[150:153], v[212:215], v[6:9]
	v_mfma_f32_16x16x32_bf16 v[2:5], v[170:173], v[212:215], v[2:5]
	s_setprio 0
	s_barrier
	s_add_i32 s41, 0, 0x18000
	s_add_i32 s52, 0, 0x1c000
	v_add_u32_e32 v142, s41, v1
	v_add_u32_e32 v170, s52, v1
	ds_read_b128 v[130:133], v142
	ds_read_b128 v[134:137], v142 offset:1024
	ds_read_b128 v[138:141], v142 offset:2048
	ds_read_b128 v[142:145], v142 offset:3072
	ds_read_b128 v[146:149], v170
	ds_read_b128 v[150:153], v170 offset:1024
	ds_read_b128 v[166:169], v170 offset:2048
	ds_read_b128 v[170:173], v170 offset:3072
	s_add_u32 s26, s26, 0x80000
	s_addc_u32 s27, s27, 0
	s_mov_b32 m0, s44
	v_lshl_add_u64 v[220:221], s[26:27], 0, v[154:155]
	ds_read_b128 v[174:177], v181 offset:32768
	ds_read_b128 v[188:191], v181 offset:33792
	ds_read_b128 v[192:195], v181 offset:34816
	ds_read_b128 v[196:199], v181 offset:35840
	ds_read_b128 v[200:203], v181 offset:36864
	ds_read_b128 v[204:207], v181 offset:37888
	ds_read_b128 v[208:211], v181 offset:38912
	ds_read_b128 v[212:215], v181 offset:39936
	global_load_lds_dwordx4 v[220:221], off
	v_lshl_add_u64 v[220:221], s[26:27], 0, v[158:159]
	s_mov_b32 m0, s45
	s_nop 0
	global_load_lds_dwordx4 v[220:221], off
	s_waitcnt vmcnt(8)
	s_waitcnt lgkmcnt(0)
	s_barrier
	s_setprio 1
	s_waitcnt lgkmcnt(0)
	v_mfma_f32_16x16x32_bf16 v[126:129], v[130:133], v[174:177], v[126:129]
	v_mfma_f32_16x16x32_bf16 v[122:125], v[138:141], v[174:177], v[122:125]
	v_mfma_f32_16x16x32_bf16 v[118:121], v[130:133], v[192:195], v[118:121]
	v_mfma_f32_16x16x32_bf16 v[114:117], v[138:141], v[192:195], v[114:117]
	v_mfma_f32_16x16x32_bf16 v[102:105], v[130:133], v[200:203], v[102:105]
	v_mfma_f32_16x16x32_bf16 v[98:101], v[138:141], v[200:203], v[98:101]
	v_mfma_f32_16x16x32_bf16 v[86:89], v[130:133], v[208:211], v[86:89]
	v_mfma_f32_16x16x32_bf16 v[82:85], v[138:141], v[208:211], v[82:85]
	v_mfma_f32_16x16x32_bf16 v[126:129], v[134:137], v[188:191], v[126:129]
	v_mfma_f32_16x16x32_bf16 v[122:125], v[142:145], v[188:191], v[122:125]
	v_mfma_f32_16x16x32_bf16 v[118:121], v[134:137], v[196:199], v[118:121]
	v_mfma_f32_16x16x32_bf16 v[114:117], v[142:145], v[196:199], v[114:117]
	v_mfma_f32_16x16x32_bf16 v[102:105], v[134:137], v[204:207], v[102:105]
	v_mfma_f32_16x16x32_bf16 v[98:101], v[142:145], v[204:207], v[98:101]
	v_mfma_f32_16x16x32_bf16 v[86:89], v[134:137], v[212:215], v[86:89]
	v_mfma_f32_16x16x32_bf16 v[82:85], v[142:145], v[212:215], v[82:85]
	s_setprio 0
	s_setprio 1
	v_mfma_f32_16x16x32_bf16 v[110:113], v[146:149], v[174:177], v[110:113]
	v_mfma_f32_16x16x32_bf16 v[106:109], v[166:169], v[174:177], v[106:109]
	v_mfma_f32_16x16x32_bf16 v[94:97], v[146:149], v[192:195], v[94:97]
	v_mfma_f32_16x16x32_bf16 v[90:93], v[166:169], v[192:195], v[90:93]
	v_mfma_f32_16x16x32_bf16 v[78:81], v[146:149], v[200:203], v[78:81]
	v_mfma_f32_16x16x32_bf16 v[74:77], v[166:169], v[200:203], v[74:77]
	v_mfma_f32_16x16x32_bf16 v[70:73], v[146:149], v[208:211], v[70:73]
	v_mfma_f32_16x16x32_bf16 v[66:69], v[166:169], v[208:211], v[66:69]
	v_mfma_f32_16x16x32_bf16 v[110:113], v[150:153], v[188:191], v[110:113]
	v_mfma_f32_16x16x32_bf16 v[106:109], v[170:173], v[188:191], v[106:109]
	v_mfma_f32_16x16x32_bf16 v[94:97], v[150:153], v[196:199], v[94:97]
	v_mfma_f32_16x16x32_bf16 v[90:93], v[170:173], v[196:199], v[90:93]
	v_mfma_f32_16x16x32_bf16 v[78:81], v[150:153], v[204:207], v[78:81]
	v_mfma_f32_16x16x32_bf16 v[74:77], v[170:173], v[204:207], v[74:77]
	v_mfma_f32_16x16x32_bf16 v[70:73], v[150:153], v[212:215], v[70:73]
	v_mfma_f32_16x16x32_bf16 v[66:69], v[170:173], v[212:215], v[66:69]
	s_setprio 0
	s_barrier
; __device__ __forceinline__ int launder(int v) { asm volatile("" : "+v"(v)); return v; }
; #define PG8_STAGE(bufoff, gbase, voff) do { _Pragma("unroll") for (int _i = 0; _i < 2; ++_i) \
;         __builtin_amdgcn_global_load_lds((const unsigned*)((const char*)(gbase) + (voff)[_i]), (LAS unsigned*)(lds + (bufoff) + ldsw + _i * 8192), 16, 0, 0); } while (0)
; #define PG8_LDA(dst, b, h) do { _Pragma("unroll") for (int m = 0; m < 4; ++m) _Pragma("unroll") for (int k = 0; k < 2; ++k) dst[m][k] = *(const LAS bf16x8*)(lds + PG8_SA(b, h) + aoff + m * 2048 + k * 1024); } while (0)
; #define PG8_MMA(ai, bj, At, Bt) do { __builtin_amdgcn_s_setprio(1); _Pragma("unroll") for (int m = 0; m < 4; ++m) _Pragma("unroll") for (int n = 0; n < 2; ++n) _Pragma("unroll") for (int k = 0; k < 2; ++k) \
;         acc[ai][bj][m][n] = __builtin_amdgcn_mfma_f32_16x16x32_bf16(Bt[n][k], At[m][k], acc[ai][bj][m][n], 0, 0, 0); __builtin_amdgcn_s_setprio(0); } while (0)
; #define PG8_WAIT_V(n) asm volatile("s_waitcnt vmcnt(" #n ")" ::: "memory")
; #define PG8_WAIT_L(n) asm volatile("s_waitcnt lgkmcnt(" #n ")" ::: "memory")
; #define PG8_BAR __builtin_amdgcn_s_barrier()
; #define PG8_SCHED __builtin_amdgcn_sched_barrier(0)
; template <class Epi>
; __device__ __forceinline__ void gemm_phase(LAS unsigned char* lds, const Gemm g, const StaticOrder& S, const Epi& E) {
;     ...
;             PG8_LDA(At, 1, 1); PG8_STAGE(PG8_SB(1, 0), b3, voffB); PG8_STAGE(PG8_SB(1, 1), b3 + hstepB, voffB); PG8_STAGE(PG8_SA(1, 0), a3, voffA);
;             PG8_WAIT_V(8); PG8_WAIT_L(0); PG8_BAR; PG8_MMA(1, 0, At, B0); PG8_MMA(1, 1, At, B1); PG8_BAR; PG8_SCHED;
;         }
;         if (wr == 0) PG8_BAR;
;         { const int l2 = launder(threadIdx.x) & 63; E(acc, cur, wr, wc, l2 & 15, l2 >> 4); }
;         if (!has_next) break;
	s_add_i32 s26, s41, s34
	v_lshl_add_u64 v[178:179], v[178:179], 0, s[84:85]
	s_mov_b32 m0, s26
	ds_read_b128 v[174:177], v181 offset:49152
	ds_read_b128 v[188:191], v181 offset:50176
	ds_read_b128 v[192:195], v181 offset:51200
	ds_read_b128 v[196:199], v181 offset:52224
	ds_read_b128 v[200:203], v181 offset:53248
	ds_read_b128 v[204:207], v181 offset:54272
	ds_read_b128 v[208:211], v181 offset:55296
	ds_read_b128 v[212:215], v181 offset:56320
	global_load_lds_dwordx4 v[178:179], off
	s_add_i32 m0, s26, 0x2000
	s_add_u32 s14, s14, 0x80080
	v_lshl_add_u64 v[178:179], v[184:185], 0, s[84:85]
	s_addc_u32 s15, s15, 0
	s_add_i32 s26, s52, s34
	global_load_lds_dwordx4 v[178:179], off
	v_lshl_add_u64 v[178:179], s[14:15], 0, v[156:157]
	s_mov_b32 m0, s26
	s_nop 0
	global_load_lds_dwordx4 v[178:179], off
	v_lshl_add_u64 v[178:179], s[14:15], 0, v[160:161]
	s_add_i32 m0, s26, 0x2000
	s_nop 0
	global_load_lds_dwordx4 v[178:179], off
	v_lshl_add_u64 v[178:179], v[216:217], 0, s[84:85]
	s_mov_b32 m0, s86
	s_nop 0
	global_load_lds_dwordx4 v[178:179], off
	v_lshl_add_u64 v[178:179], v[218:219], 0, s[84:85]
	s_mov_b32 m0, s87
	s_nop 0
	global_load_lds_dwordx4 v[178:179], off
	s_waitcnt vmcnt(8)
	s_waitcnt lgkmcnt(0)
	s_barrier
	s_setprio 1
	s_waitcnt lgkmcnt(0)
	v_mfma_f32_16x16x32_bf16 v[62:65], v[130:133], v[174:177], v[62:65]
	v_mfma_f32_16x16x32_bf16 v[58:61], v[138:141], v[174:177], v[58:61]
	v_mfma_f32_16x16x32_bf16 v[54:57], v[130:133], v[192:195], v[54:57]
	v_mfma_f32_16x16x32_bf16 v[50:53], v[138:141], v[192:195], v[50:53]
	v_mfma_f32_16x16x32_bf16 v[46:49], v[130:133], v[200:203], v[46:49]
	v_mfma_f32_16x16x32_bf16 v[38:41], v[138:141], v[200:203], v[38:41]
	v_mfma_f32_16x16x32_bf16 v[30:33], v[130:133], v[208:211], v[30:33]
	v_mfma_f32_16x16x32_bf16 v[22:25], v[138:141], v[208:211], v[22:25]
	v_mfma_f32_16x16x32_bf16 v[62:65], v[134:137], v[188:191], v[62:65]
	v_mfma_f32_16x16x32_bf16 v[58:61], v[142:145], v[188:191], v[58:61]
	v_mfma_f32_16x16x32_bf16 v[54:57], v[134:137], v[196:199], v[54:57]
	v_mfma_f32_16x16x32_bf16 v[50:53], v[142:145], v[196:199], v[50:53]
	v_mfma_f32_16x16x32_bf16 v[46:49], v[134:137], v[204:207], v[46:49]
	v_mfma_f32_16x16x32_bf16 v[38:41], v[142:145], v[204:207], v[38:41]
	v_mfma_f32_16x16x32_bf16 v[30:33], v[134:137], v[212:215], v[30:33]
	v_mfma_f32_16x16x32_bf16 v[22:25], v[142:145], v[212:215], v[22:25]
	s_setprio 0
	s_setprio 1
	v_mfma_f32_16x16x32_bf16 v[42:45], v[146:149], v[174:177], v[42:45]
	v_mfma_f32_16x16x32_bf16 v[34:37], v[166:169], v[174:177], v[34:37]
	v_mfma_f32_16x16x32_bf16 v[26:29], v[146:149], v[192:195], v[26:29]
	v_mfma_f32_16x16x32_bf16 v[18:21], v[166:169], v[192:195], v[18:21]
	v_mfma_f32_16x16x32_bf16 v[14:17], v[146:149], v[200:203], v[14:17]
	v_mfma_f32_16x16x32_bf16 v[10:13], v[166:169], v[200:203], v[10:13]
	v_mfma_f32_16x16x32_bf16 v[6:9], v[146:149], v[208:211], v[6:9]
	v_mfma_f32_16x16x32_bf16 v[2:5], v[166:169], v[208:211], v[2:5]
	v_mfma_f32_16x16x32_bf16 v[42:45], v[150:153], v[188:191], v[42:45]
	v_mfma_f32_16x16x32_bf16 v[34:37], v[170:173], v[188:191], v[34:37]
	v_mfma_f32_16x16x32_bf16 v[26:29], v[150:153], v[196:199], v[26:29]
	v_mfma_f32_16x16x32_bf16 v[18:21], v[170:173], v[196:199], v[18:21]
	v_mfma_f32_16x16x32_bf16 v[14:17], v[150:153], v[204:207], v[14:17]
	v_mfma_f32_16x16x32_bf16 v[10:13], v[170:173], v[204:207], v[10:13]
	v_mfma_f32_16x16x32_bf16 v[6:9], v[150:153], v[212:215], v[6:9]
	v_mfma_f32_16x16x32_bf16 v[2:5], v[170:173], v[212:215], v[2:5]
	s_setprio 0
	s_barrier
	s_add_i32 s40, s40, 2
	s_add_u32 s24, s24, 0x100
	s_addc_u32 s25, s25, 0
	s_add_u32 s19, s19, 0x100
	s_addc_u32 s33, s33, 0
	s_cmp_gt_u32 s40, 29
	s_cbranch_scc0 .LBB0_2332
	s_cmp_ge_u32 s74, 16
	s_cbranch_scc1 .Lwpf_f
	s_lshl_b32 s100, s74, 9
	v_add_u32_e32 v130, s100, v246
	v_lshrrev_b32_e32 v131, 2, v130
	v_and_b32_e32 v130, 3, v130
	v_lshlrev_b32_e32 v130, 7, v130
	v_lshl_add_u32 v130, v131, 12, v130
	v_readlane_b32 s100, v255, 42
	s_nop 3
	s_mov_b32 s101, 0x16900000
	s_cmp_eq_u32 s100, 1
	s_cselect_b32 s101, 0x15100000, s101
	s_cmp_eq_u32 s100, 0
	s_cselect_b32 s101, 0x13700000, s101
	s_add_u32 s100, s38, s101
	s_addc_u32 s101, s39, 0
	s_mov_b32 m0, 0x21000
	s_nop 0
	global_load_lds_dword v130, s[100:101]
.Lwpf_f:
	s_and_b64 vcc, exec, s[12:13]
	s_cbranch_vccz .LBB0_2335
	s_barrier
; __device__ __forceinline__ float shx(float v, int o, int lane) { return __builtin_bit_cast(float, __builtin_amdgcn_ds_bpermute((lane ^ o) << 2, __builtin_bit_cast(int, v))); }
; __device__ __forceinline__ void rows_rstd(const float* ssq, int row0  , int fr, int fq, float (&rs)[8]) {
;     const int lane = fq * 16 + fr; f32x4 p[8];
;     const float* b0 = ssq + (size_t)row0 * 16 + fq * 4;
; #pragma unroll
;     for (int r = 0; r < 8; ++r) p[r] = *(const f32x4*)(b0 + (r >> 2) * (HALF * 16) + (r & 3) * 256);
; #pragma unroll
;     for (int r = 0; r < 8; ++r) { float v = (p[r][0] + p[r][1]) + (p[r][2] + p[r][3]); v += shx(v, 16, lane); v += shx(v, 32, lane); rs[r] = rsqrtf(v * (1.0f / 2048.0f) + 1e-6f); }
; }
;     __device__ __forceinline__ void operator()(f32x4 (&acc)[2][2][4][2], const Unit& u, int wr, int wc, int fr, int fq) const {
;         const int col0 = u.pn * BM + wc * 32 + 8 * fq;
;         float s[2][4];
;         { float rsv[8]; rows_rstd(ssq_in, u.pm * BM + wr * 64 + fr, fr, fq, rsv);
; #pragma unroll
;             for (int r = 0; r < 8; ++r)
; #pragma unroll
;                 for (int c = 0; c < 4; ++c) acc[r >> 2][c >> 1][r & 3][c & 1] = acc[r >> 2][c >> 1][r & 3][c & 1] * rsv[r]; }
.LBB0_2335:
	v_mov_b32_e32 v183, v246
	s_lshl_b32 s1, s8, 8
	s_add_i32 s3, s1, s68
	v_and_b32_e32 v184, 15, v183
	v_or_b32_e32 v172, s3, v184
	v_ashrrev_i32_e32 v173, 31, v172
	v_readlane_b32 s8, v254, 13
	v_bfe_u32 v185, v183, 4, 2
	v_lshlrev_b64 v[130:131], 6, v[172:173]
	v_readlane_b32 s9, v254, 14
	v_lshlrev_b32_e32 v132, 4, v185
	v_mov_b32_e32 v133, v0
	v_lshl_add_u64 v[130:131], s[8:9], 0, v[130:131]
	v_lshl_add_u64 v[130:131], v[130:131], 0, v[132:133]
	global_load_dwordx4 v[174:177], v[130:131], off
	global_load_dwordx4 v[188:191], v[130:131], off offset:1024
	global_load_dwordx4 v[150:153], v[130:131], off offset:2048
	global_load_dwordx4 v[146:149], v[130:131], off offset:3072
	v_add_co_u32_e32 v130, vcc, s63, v130
	v_lshlrev_b32_e32 v166, 6, v185
	s_nop 0
	v_addc_co_u32_e32 v131, vcc, 0, v131, vcc
	global_load_dwordx4 v[142:145], v[130:131], off
	global_load_dwordx4 v[138:141], v[130:131], off offset:1024
	global_load_dwordx4 v[134:137], v[130:131], off offset:2048
	s_nop 0
	global_load_dwordx4 v[130:133], v[130:131], off offset:3072
	v_lshlrev_b32_e32 v167, 2, v184
	v_bitop3_b32 v169, v166, 64, v167 bitop3:0x36
	v_bitop3_b32 v167, v166, s71, v167 bitop3:0x36
	s_mov_b32 s8, 0x358637bd
	v_mov_b32_e32 v182, v246
	v_or_b32_e32 v242, 32, v172
	v_or_b32_e32 v228, 48, v172
	v_ashrrev_i32_e32 v243, 31, v242
	v_ashrrev_i32_e32 v229, 31, v228
	s_waitcnt vmcnt(0)
	v_mov_b32_e32 v170, v175
	v_mov_b32_e32 v171, v176
	v_mov_b32_e32 v175, v177
	v_pk_add_f32 v[170:171], v[170:171], v[174:175]
	v_mov_b32_e32 v174, v189
	v_mov_b32_e32 v175, v190
	v_mov_b32_e32 v189, v191
	v_pk_add_f32 v[174:175], v[174:175], v[188:189]
	v_mov_b32_e32 v177, v170
	v_mov_b32_e32 v176, v174
	v_mov_b32_e32 v170, v175
	v_pk_add_f32 v[170:171], v[176:177], v[170:171]
	ds_bpermute_b32 v175, v169, v171
	ds_bpermute_b32 v174, v169, v170
	s_waitcnt lgkmcnt(0)
	v_pk_add_f32 v[170:171], v[170:171], v[174:175]
	ds_bpermute_b32 v175, v167, v171
	ds_bpermute_b32 v174, v167, v170
	s_waitcnt lgkmcnt(0)
	v_pk_add_f32 v[174:175], v[170:171], v[174:175]
	v_mov_b64_e32 v[170:171], s[8:9]
	v_pk_fma_f32 v[174:175], v[174:175], s[2:3], v[170:171] op_sel_hi:[1,0,0]
	s_nop 0
	v_mul_f32_e32 v166, 0x4b800000, v175
	v_cmp_gt_f32_e64 s[8:9], s46, v175
	v_cmp_gt_f32_e32 vcc, s46, v174
	s_nop 0
	v_cndmask_b32_e64 v166, v175, v166, s[8:9]
	v_rsq_f32_e32 v166, v166
	v_mov_b32_e32 v175, v152
	v_mov_b32_e32 v152, v147
	v_mov_b32_e32 v147, v149
	v_mul_f32_e32 v168, 0x45800000, v166
	v_cndmask_b32_e64 v168, v166, v168, s[8:9]
	v_mul_f32_e32 v166, 0x4b800000, v174
	v_cndmask_b32_e32 v166, v174, v166, vcc
	v_rsq_f32_e32 v166, v166
	v_pk_mul_f32 v[252:253], v[128:129], v[168:169] op_sel_hi:[1,0]
	v_pk_mul_f32 v[178:179], v[126:127], v[168:169] op_sel_hi:[1,0]
	v_pk_mul_f32 v[248:249], v[124:125], v[168:169] op_sel_hi:[1,0]
	v_mul_f32_e32 v174, 0x45800000, v166
	v_cndmask_b32_e32 v166, v166, v174, vcc
	v_mov_b32_e32 v174, v151
	v_mov_b32_e32 v151, v153
	v_mov_b32_e32 v153, v148
	v_pk_add_f32 v[150:151], v[174:175], v[150:151]
	v_pk_add_f32 v[146:147], v[152:153], v[146:147]
	v_mov_b32_e32 v149, v150
	v_mov_b32_e32 v148, v146
	v_mov_b32_e32 v150, v147
	v_pk_add_f32 v[146:147], v[148:149], v[150:151]
	ds_bpermute_b32 v149, v169, v147
	ds_bpermute_b32 v148, v169, v146
	v_mov_b32_e32 v150, v143
	v_mov_b32_e32 v151, v144
	v_mov_b32_e32 v143, v145
	v_mov_b32_e32 v144, v139
	v_mov_b32_e32 v145, v140
	v_mov_b32_e32 v139, v141
	v_pk_add_f32 v[142:143], v[150:151], v[142:143]
	v_pk_add_f32 v[138:139], v[144:145], v[138:139]
	s_waitcnt lgkmcnt(0)
	v_pk_add_f32 v[146:147], v[146:147], v[148:149]
	v_mov_b32_e32 v140, v138
	v_mov_b32_e32 v141, v142
	v_mov_b32_e32 v142, v139
	ds_bpermute_b32 v149, v167, v147
	ds_bpermute_b32 v148, v167, v146
	v_pk_add_f32 v[138:139], v[140:141], v[142:143]
	ds_bpermute_b32 v141, v169, v139
	ds_bpermute_b32 v140, v169, v138
	v_mov_b32_e32 v142, v135
	v_mov_b32_e32 v143, v136
	v_mov_b32_e32 v135, v137
	v_mov_b32_e32 v136, v131
	v_mov_b32_e32 v137, v132
	v_mov_b32_e32 v131, v133
	s_waitcnt lgkmcnt(2)
	v_pk_add_f32 v[146:147], v[146:147], v[148:149]
	v_pk_add_f32 v[134:135], v[142:143], v[134:135]
	v_pk_add_f32 v[130:131], v[136:137], v[130:131]
	v_pk_fma_f32 v[146:147], v[146:147], s[2:3], v[170:171] op_sel_hi:[1,0,0]
	s_waitcnt lgkmcnt(0)
	v_pk_add_f32 v[138:139], v[138:139], v[140:141]
	v_mov_b32_e32 v132, v130
	v_mov_b32_e32 v133, v134
	v_mov_b32_e32 v134, v131
	v_mul_f32_e32 v148, 0x4b800000, v147
	v_cmp_gt_f32_e64 s[8:9], s46, v147
	ds_bpermute_b32 v141, v167, v139
	ds_bpermute_b32 v140, v167, v138
	v_pk_add_f32 v[130:131], v[132:133], v[134:135]
	v_cndmask_b32_e64 v147, v147, v148, s[8:9]
	ds_bpermute_b32 v133, v169, v131
	ds_bpermute_b32 v132, v169, v130
	v_rsq_f32_e32 v147, v147
	s_waitcnt lgkmcnt(2)
	v_pk_add_f32 v[138:139], v[138:139], v[140:141]
	v_cmp_gt_f32_e32 vcc, s46, v146
	v_pk_fma_f32 v[138:139], v[138:139], s[2:3], v[170:171] op_sel_hi:[1,0,0]
	v_mul_f32_e32 v148, 0x45800000, v147
	s_waitcnt lgkmcnt(0)
	v_pk_add_f32 v[130:131], v[130:131], v[132:133]
	v_cndmask_b32_e64 v148, v147, v148, s[8:9]
	v_mul_f32_e32 v147, 0x4b800000, v146
	v_mul_f32_e32 v140, 0x4b800000, v139
	v_cmp_gt_f32_e64 s[8:9], s46, v139
	ds_bpermute_b32 v133, v167, v131
	ds_bpermute_b32 v132, v167, v130
	v_cndmask_b32_e32 v146, v146, v147, vcc
	v_cndmask_b32_e64 v139, v139, v140, s[8:9]
	v_rsq_f32_e32 v146, v146
	v_rsq_f32_e32 v139, v139
	s_waitcnt lgkmcnt(0)
;     __device__ __forceinline__ void operator()(f32x4 (&acc)[2][2][4][2], const Unit& u, int wr, int wc, int fr, int fq) const {
;     ...
;         { float rsv[8]; rows_rstd(ssq_in, u.pm * BM + wr * 64 + fr, fr, fq, rsv);
; #pragma unroll
;             for (int r = 0; r < 8; ++r)
; #pragma unroll
;                 for (int c = 0; c < 4; ++c) acc[r >> 2][c >> 1][r & 3][c & 1] = acc[r >> 2][c >> 1][r & 3][c & 1] * rsv[r]; }
;         f32x4 cur[2][4], nxt[2][4]; u32x2 pcur[4], pnxt[4];
; #pragma unroll
;         for (int q = 0; q < 2; ++q)
; #pragma unroll
;             for (int c = 0; c < 4; ++c) cur[q][c] = *(const f32x4*)(h + (size_t)EPI_ROW(q) * D + col0 + (c >> 1) * HALF + (c & 1) * 4);
; #pragma unroll
;         for (int c = 0; c < 4; ++c) pcur[c] = *(const u32x2*)(pp + (size_t)EPI_ROW(0) * D + col0 + (c >> 1) * HALF + (c & 1) * 4);
	v_pk_add_f32 v[130:131], v[130:131], v[132:133]
	v_pk_mul_f32 v[250:251], v[122:123], v[168:169] op_sel_hi:[1,0]
	v_mul_f32_e32 v147, 0x45800000, v146
	v_mul_f32_e32 v140, 0x45800000, v139
	v_pk_fma_f32 v[130:131], v[130:131], s[2:3], v[170:171] op_sel_hi:[1,0,0]
	v_cndmask_b32_e32 v146, v146, v147, vcc
	v_cmp_gt_f32_e32 vcc, s46, v138
	v_cndmask_b32_e64 v140, v139, v140, s[8:9]
	v_mul_f32_e32 v139, 0x4b800000, v138
	v_mul_f32_e32 v132, 0x4b800000, v131
	v_cmp_gt_f32_e64 s[8:9], s46, v131
	v_cndmask_b32_e32 v138, v138, v139, vcc
	v_rsq_f32_e32 v138, v138
	v_cndmask_b32_e64 v131, v131, v132, s[8:9]
	v_rsq_f32_e32 v131, v131
	s_lshl_b32 s3, s0, 8
	v_mul_f32_e32 v139, 0x45800000, v138
	v_cndmask_b32_e32 v138, v138, v139, vcc
	v_mul_f32_e32 v132, 0x45800000, v131
	v_cmp_gt_f32_e32 vcc, s46, v130
	v_cndmask_b32_e64 v132, v131, v132, s[8:9]
	v_mul_f32_e32 v131, 0x4b800000, v130
	v_cndmask_b32_e32 v130, v130, v131, vcc
	v_rsq_f32_e32 v130, v130
	s_or_b32 s3, s3, s69
	v_pk_mul_f32 v[244:245], v[112:113], v[168:169] op_sel_hi:[1,0]
	v_pk_mul_f32 v[246:247], v[110:111], v[168:169] op_sel_hi:[1,0]
	v_mul_f32_e32 v131, 0x45800000, v130
	v_cndmask_b32_e32 v152, v130, v131, vcc
	v_pk_mul_f32 v[238:239], v[108:109], v[168:169] op_sel_hi:[1,0]
	v_pk_mul_f32 v[240:241], v[106:107], v[168:169] op_sel_hi:[1,0]
	v_pk_mul_f32 v[234:235], v[120:121], v[166:167] op_sel_hi:[1,0]
	v_pk_mul_f32 v[236:237], v[118:119], v[166:167] op_sel_hi:[1,0]
	v_pk_mul_f32 v[222:223], v[116:117], v[166:167] op_sel_hi:[1,0]
	v_pk_mul_f32 v[232:233], v[114:115], v[166:167] op_sel_hi:[1,0]
	v_pk_mul_f32 v[96:97], v[96:97], v[166:167] op_sel_hi:[1,0]
	v_pk_mul_f32 v[94:95], v[94:95], v[166:167] op_sel_hi:[1,0]
	v_pk_mul_f32 v[92:93], v[92:93], v[166:167] op_sel_hi:[1,0]
	v_pk_mul_f32 v[90:91], v[90:91], v[166:167] op_sel_hi:[1,0]
	v_pk_mul_f32 v[224:225], v[104:105], v[148:149] op_sel_hi:[1,0]
	v_pk_mul_f32 v[226:227], v[102:103], v[148:149] op_sel_hi:[1,0]
	v_pk_mul_f32 v[126:127], v[100:101], v[148:149] op_sel_hi:[1,0]
	v_pk_mul_f32 v[128:129], v[98:99], v[148:149] op_sel_hi:[1,0]
	v_pk_mul_f32 v[122:123], v[80:81], v[148:149] op_sel_hi:[1,0]
	v_pk_mul_f32 v[124:125], v[78:79], v[148:149] op_sel_hi:[1,0]
	v_pk_mul_f32 v[114:115], v[76:77], v[148:149] op_sel_hi:[1,0]
	v_pk_mul_f32 v[116:117], v[74:75], v[148:149] op_sel_hi:[1,0]
	v_pk_mul_f32 v[110:111], v[88:89], v[146:147] op_sel_hi:[1,0]
	v_pk_mul_f32 v[112:113], v[86:87], v[146:147] op_sel_hi:[1,0]
	v_pk_mul_f32 v[106:107], v[84:85], v[146:147] op_sel_hi:[1,0]
	v_pk_mul_f32 v[108:109], v[82:83], v[146:147] op_sel_hi:[1,0]
	v_pk_mul_f32 v[102:103], v[72:73], v[146:147] op_sel_hi:[1,0]
	v_pk_mul_f32 v[104:105], v[70:71], v[146:147] op_sel_hi:[1,0]
	v_pk_mul_f32 v[98:99], v[68:69], v[146:147] op_sel_hi:[1,0]
	v_pk_mul_f32 v[100:101], v[66:67], v[146:147] op_sel_hi:[1,0]
	v_pk_mul_f32 v[218:219], v[64:65], v[140:141] op_sel_hi:[1,0]
	v_pk_mul_f32 v[220:221], v[62:63], v[140:141] op_sel_hi:[1,0]
	v_pk_mul_f32 v[214:215], v[60:61], v[140:141] op_sel_hi:[1,0]
	v_pk_mul_f32 v[216:217], v[58:59], v[140:141] op_sel_hi:[1,0]
	v_pk_mul_f32 v[210:211], v[44:45], v[140:141] op_sel_hi:[1,0]
	v_pk_mul_f32 v[212:213], v[42:43], v[140:141] op_sel_hi:[1,0]
	v_pk_mul_f32 v[206:207], v[36:37], v[140:141] op_sel_hi:[1,0]
	v_pk_mul_f32 v[208:209], v[34:35], v[140:141] op_sel_hi:[1,0]
	v_pk_mul_f32 v[202:203], v[56:57], v[138:139] op_sel_hi:[1,0]
	v_pk_mul_f32 v[204:205], v[54:55], v[138:139] op_sel_hi:[1,0]
	v_pk_mul_f32 v[196:197], v[52:53], v[138:139] op_sel_hi:[1,0]
	v_pk_mul_f32 v[200:201], v[50:51], v[138:139] op_sel_hi:[1,0]
	v_pk_mul_f32 v[192:193], v[28:29], v[138:139] op_sel_hi:[1,0]
	v_pk_mul_f32 v[194:195], v[26:27], v[138:139] op_sel_hi:[1,0]
	v_pk_mul_f32 v[188:189], v[20:21], v[138:139] op_sel_hi:[1,0]
	v_pk_mul_f32 v[190:191], v[18:19], v[138:139] op_sel_hi:[1,0]
	v_pk_mul_f32 v[174:175], v[48:49], v[132:133] op_sel_hi:[1,0]
	v_pk_mul_f32 v[176:177], v[46:47], v[132:133] op_sel_hi:[1,0]
	v_pk_mul_f32 v[168:169], v[40:41], v[132:133] op_sel_hi:[1,0]
	v_pk_mul_f32 v[170:171], v[38:39], v[132:133] op_sel_hi:[1,0]
	v_pk_mul_f32 v[150:151], v[16:17], v[132:133] op_sel_hi:[1,0]
	v_pk_mul_f32 v[166:167], v[14:15], v[132:133] op_sel_hi:[1,0]
	v_pk_mul_f32 v[146:147], v[12:13], v[132:133] op_sel_hi:[1,0]
	v_pk_mul_f32 v[148:149], v[10:11], v[132:133] op_sel_hi:[1,0]
	v_pk_mul_f32 v[142:143], v[32:33], v[152:153] op_sel_hi:[1,0]
	v_pk_mul_f32 v[144:145], v[30:31], v[152:153] op_sel_hi:[1,0]
	v_pk_mul_f32 v[138:139], v[24:25], v[152:153] op_sel_hi:[1,0]
	v_pk_mul_f32 v[140:141], v[22:23], v[152:153] op_sel_hi:[1,0]
	v_pk_mul_f32 v[134:135], v[8:9], v[152:153] op_sel_hi:[1,0]
	v_pk_mul_f32 v[136:137], v[6:7], v[152:153] op_sel_hi:[1,0]
	v_pk_mul_f32 v[130:131], v[4:5], v[152:153] op_sel_hi:[1,0]
	v_pk_mul_f32 v[132:133], v[2:3], v[152:153] op_sel_hi:[1,0]
	v_lshl_or_b32 v152, v185, 3, s3
	v_ashrrev_i32_e32 v153, 31, v152
	v_or_b32_e32 v84, 16, v172
	v_lshl_add_u64 v[118:119], v[152:153], 2, s[36:37]
	v_lshlrev_b64 v[2:3], 13, v[172:173]
	v_ashrrev_i32_e32 v85, 31, v84
	v_lshlrev_b64 v[18:19], 12, v[172:173]
	v_lshl_add_u64 v[86:87], v[118:119], 0, v[2:3]
	v_lshlrev_b64 v[2:3], 13, v[84:85]
	v_lshl_add_u64 v[18:19], s[56:57], 0, v[18:19]
	v_lshlrev_b64 v[198:199], 1, v[152:153]
	v_lshl_add_u64 v[82:83], v[118:119], 0, v[2:3]
	v_lshl_add_u64 v[18:19], v[18:19], 0, v[198:199]
	global_load_dwordx4 v[66:69], v[86:87], off offset:16
	global_load_dwordx4 v[78:81], v[86:87], off
	global_load_dwordx4 v[54:57], v[86:87], off offset:528
	global_load_dwordx4 v[62:65], v[86:87], off offset:512
	global_load_dwordx4 v[6:9], v[82:83], off offset:16
; __device__ __forceinline__ float sigmoidf_(float x) { return __builtin_amdgcn_rcpf(1.0f + __expf(-x)); }
; __device__ __forceinline__ float ssq4(const f32x4 o) { return (o[0] * o[0] + o[1] * o[1]) + (o[2] * o[2] + o[3] * o[3]); }
;     __device__ __forceinline__ void operator()(f32x4 (&acc)[2][2][4][2], const Unit& u, int wr, int wc, int fr, int fq) const {
;     ...
;         for (int k = 0; k < 4; ++k) {
;             if (k < 3) {
; #pragma unroll
;                 for (int q = 0; q < 2; ++q)
; #pragma unroll
;                     for (int c = 0; c < 4; ++c) nxt[q][c] = *(const f32x4*)(h + (size_t)EPI_ROW(2 * k + 2 + q) * D + col0 + (c >> 1) * HALF + (c & 1) * 4);
;             }
; #pragma unroll
;             for (int q = 0; q < 2; ++q) { const int r = 2 * k + q, ai = r >> 2, m = r & 3; const size_t off = (size_t)EPI_ROW(r) * D + col0; float sr = 0.f;
;                 if (r < 7) {
; #pragma unroll
;                     for (int c = 0; c < 4; ++c) pnxt[c] = *(const u32x2*)(pp + (size_t)EPI_ROW(r + 1) * D + col0 + (c >> 1) * HALF + (c & 1) * 4);
;                 }
;                 asm volatile("" ::: "memory");
; #pragma unroll
;                 for (int bj = 0; bj < 2; ++bj) { f32x4 o2[2];
; #pragma unroll
;                     for (int n = 0; n < 2; ++n) { const f32x4 b = cur[q][2 * bj + n]; const u32x2 qw = pcur[2 * bj + n];
;                         const f32x4 pq = (f32x4){bflo(qw.x), bfhi(qw.x), bflo(qw.y), bfhi(qw.y)}; const f32x4 a = acc[ai][bj][m][n];
; #pragma unroll
;                         for (int j = 0; j < 4; ++j) o2[n][j] = b[j] + pq[j] * sigmoidf_(a[j]); }
;                     *(f32x4*)(h + off + bj * HALF) = o2[0]; *(f32x4*)(h + off + bj * HALF + 4) = o2[1];
;                     if (!LAST) { u32x4 w; w.x = cvt_pk_bf16(o2[0][0], o2[0][1]); w.y = cvt_pk_bf16(o2[0][2], o2[0][3]); w.z = cvt_pk_bf16(o2[1][0], o2[1][1]); w.w = cvt_pk_bf16(o2[1][2], o2[1][3]);
;                         *(u32x4*)(hb + off + bj * HALF) = w; sr += ssq4(o2[0]) + ssq4(o2[1]); } }
;                 s[ai][m] = sr;
	global_load_dwordx4 v[2:5], v[82:83], off
	global_load_dwordx4 v[14:17], v[82:83], off offset:528
	global_load_dwordx4 v[10:13], v[82:83], off offset:512
	global_load_dwordx4 v[74:77], v[18:19], off
	global_load_dwordx4 v[70:73], v[18:19], off offset:256
	v_lshlrev_b64 v[50:51], 11, v[172:173]
	v_mul_f32_e32 v173, 0xbfb8aa3b, v178
	v_exp_f32_e32 v173, v173
	v_lshl_add_u64 v[88:89], v[50:51], 0, v[152:153]
	v_lshlrev_b64 v[50:51], 12, v[84:85]
	v_lshlrev_b64 v[18:19], 13, v[242:243]
	v_add_f32_e32 v173, 1.0, v173
	v_rcp_f32_e32 v178, v173
	v_mul_f32_e32 v173, 0xbfb8aa3b, v179
	v_exp_f32_e32 v173, v173
	v_lshlrev_b64 v[34:35], 13, v[228:229]
	v_lshl_add_u64 v[50:51], s[56:57], 0, v[50:51]
	v_lshl_add_u64 v[230:231], v[118:119], 0, v[18:19]
	v_add_f32_e32 v173, 1.0, v173
	v_rcp_f32_e32 v179, v173
	v_lshl_add_u64 v[120:121], v[118:119], 0, v[34:35]
	v_lshl_add_u64 v[50:51], v[50:51], 0, v[198:199]
	global_load_dwordx4 v[22:25], v[230:231], off offset:16
	global_load_dwordx4 v[18:21], v[230:231], off
	global_load_dwordx4 v[30:33], v[230:231], off offset:528
	global_load_dwordx4 v[26:29], v[230:231], off offset:512
	global_load_dwordx4 v[38:41], v[120:121], off offset:16
	global_load_dwordx4 v[34:37], v[120:121], off
	global_load_dwordx4 v[46:49], v[120:121], off offset:528
	global_load_dwordx4 v[42:45], v[120:121], off offset:512
	global_load_dwordx4 v[58:61], v[50:51], off
	s_nop 0
	global_load_dwordx4 v[50:53], v[50:51], off offset:256
	v_lshl_add_u64 v[88:89], v[88:89], 1, s[54:55]
	v_mul_f32_e32 v173, 0xbfb8aa3b, v226
	v_exp_f32_e32 v173, v173
	v_mul_f32_e32 v176, 0xbfb8aa3b, v176
	v_mul_f32_e32 v177, 0xbfb8aa3b, v177
	v_exp_f32_e32 v176, v176
	v_add_f32_e32 v173, 1.0, v173
	v_rcp_f32_e32 v226, v173
	v_mul_f32_e32 v173, 0xbfb8aa3b, v227
	v_exp_f32_e32 v173, v173
	v_exp_f32_e32 v177, v177
	v_add_f32_e32 v176, 1.0, v176
	v_rcp_f32_e32 v176, v176
	v_add_f32_e32 v173, 1.0, v173
	v_rcp_f32_e32 v227, v173
	v_add_f32_e32 v177, 1.0, v177
	v_rcp_f32_e32 v177, v177
	v_cmp_eq_u32_e32 vcc, 0, v185
	s_waitcnt vmcnt(11)
	v_lshlrev_b32_e32 v186, 16, v74
	v_and_b32_e32 v187, 0xffff0000, v74
	v_mul_f32_e32 v74, 0xbfb8aa3b, v252
	v_exp_f32_e32 v74, v74
	v_pk_fma_f32 v[78:79], v[178:179], v[186:187], v[78:79]
	v_add_f32_e32 v74, 1.0, v74
	v_rcp_f32_e32 v178, v74
	v_mul_f32_e32 v74, 0xbfb8aa3b, v253
	v_exp_f32_e32 v74, v74
	s_nop 0
	v_add_f32_e32 v74, 1.0, v74
	v_rcp_f32_e32 v179, v74
	v_lshlrev_b32_e32 v74, 16, v75
	v_and_b32_e32 v75, 0xffff0000, v75
	v_pk_fma_f32 v[80:81], v[178:179], v[74:75], v[80:81]
	v_mul_f32_e32 v74, 0xbfb8aa3b, v250
	v_mul_f32_e32 v75, 0xbfb8aa3b, v251
	v_exp_f32_e32 v74, v74
	v_exp_f32_e32 v75, v75
	v_lshlrev_b32_e32 v178, 16, v76
	v_and_b32_e32 v179, 0xffff0000, v76
	v_add_f32_e32 v74, 1.0, v74
	v_add_f32_e32 v75, 1.0, v75
	v_rcp_f32_e32 v74, v74
	v_rcp_f32_e32 v75, v75
	v_lshlrev_b32_e32 v76, 16, v77
	v_and_b32_e32 v77, 0xffff0000, v77
	v_pk_fma_f32 v[66:67], v[74:75], v[178:179], v[66:67]
	v_mul_f32_e32 v74, 0xbfb8aa3b, v248
	v_mul_f32_e32 v75, 0xbfb8aa3b, v249
	v_exp_f32_e32 v74, v74
	v_exp_f32_e32 v75, v75
	v_mul_f32_e32 v179, 0xbfb8aa3b, v220
	v_exp_f32_e32 v179, v179
	v_add_f32_e32 v74, 1.0, v74
	v_add_f32_e32 v75, 1.0, v75
	v_rcp_f32_e32 v74, v74
	v_rcp_f32_e32 v75, v75
	v_add_f32_e32 v179, 1.0, v179
	v_rcp_f32_e32 v220, v179
	v_mul_f32_e32 v179, 0xbfb8aa3b, v221
	v_pk_fma_f32 v[68:69], v[74:75], v[76:77], v[68:69]
	v_cvt_pk_bf16_f32 v74, v78, v79
	v_cvt_pk_bf16_f32 v75, v80, v81
	v_cvt_pk_bf16_f32 v76, v66, v67
	v_cvt_pk_bf16_f32 v77, v68, v69
	global_store_dwordx4 v[86:87], v[78:81], off
	global_store_dwordx4 v[86:87], v[66:69], off offset:16
	global_store_dwordx4 v[88:89], v[74:77], off
	v_exp_f32_e32 v179, v179
	s_nop 0
	v_pk_mul_f32 v[74:75], v[78:79], v[78:79]
	v_pk_mul_f32 v[78:79], v[66:67], v[66:67]
	v_mul_f32_e32 v66, 0xbfb8aa3b, v246
	v_mul_f32_e32 v67, 0xbfb8aa3b, v247
	v_exp_f32_e32 v66, v66
	v_exp_f32_e32 v67, v67
	v_pk_mul_f32 v[76:77], v[80:81], v[80:81]
	v_pk_mul_f32 v[80:81], v[68:69], v[68:69]
	v_add_f32_e32 v66, 1.0, v66
	v_add_f32_e32 v67, 1.0, v67
	v_rcp_f32_e32 v66, v66
	v_rcp_f32_e32 v67, v67
	s_waitcnt vmcnt(13)
	v_lshlrev_b32_e32 v68, 16, v70
	v_and_b32_e32 v69, 0xffff0000, v70
	v_add_f32_e32 v179, 1.0, v179
	v_pk_fma_f32 v[62:63], v[66:67], v[68:69], v[62:63]
	v_mul_f32_e32 v66, 0xbfb8aa3b, v244
	v_mul_f32_e32 v67, 0xbfb8aa3b, v245
	v_exp_f32_e32 v66, v66
	v_exp_f32_e32 v67, v67
	v_lshlrev_b32_e32 v68, 16, v71
	v_and_b32_e32 v69, 0xffff0000, v71
	v_add_f32_e32 v66, 1.0, v66
	v_add_f32_e32 v67, 1.0, v67
	v_rcp_f32_e32 v66, v66
	v_rcp_f32_e32 v67, v67
	v_rcp_f32_e32 v221, v179
	v_mul_f32_e32 v179, 0xbfb8aa3b, v204
	v_exp_f32_e32 v179, v179
	v_pk_fma_f32 v[64:65], v[66:67], v[68:69], v[64:65]
	v_mul_f32_e32 v66, 0xbfb8aa3b, v240
	v_mul_f32_e32 v67, 0xbfb8aa3b, v241
	v_exp_f32_e32 v66, v66
	v_exp_f32_e32 v67, v67
	v_lshlrev_b32_e32 v68, 16, v72
	v_and_b32_e32 v69, 0xffff0000, v72
	v_add_f32_e32 v66, 1.0, v66
	v_add_f32_e32 v67, 1.0, v67
	v_rcp_f32_e32 v66, v66
	v_rcp_f32_e32 v67, v67
	v_add_f32_e32 v179, 1.0, v179
	v_rcp_f32_e32 v204, v179
	v_mul_f32_e32 v179, 0xbfb8aa3b, v205
	v_pk_fma_f32 v[54:55], v[66:67], v[68:69], v[54:55]
	v_mul_f32_e32 v66, 0xbfb8aa3b, v238
	v_mul_f32_e32 v67, 0xbfb8aa3b, v239
	v_exp_f32_e32 v66, v66
	v_exp_f32_e32 v67, v67
	v_lshlrev_b32_e32 v68, 16, v73
	v_and_b32_e32 v69, 0xffff0000, v73
	v_add_f32_e32 v66, 1.0, v66
	v_add_f32_e32 v67, 1.0, v67
	v_rcp_f32_e32 v66, v66
	v_rcp_f32_e32 v67, v67
	v_exp_f32_e32 v179, v179
	v_pk_fma_f32 v[56:57], v[66:67], v[68:69], v[56:57]
	global_store_dwordx4 v[86:87], v[62:65], off offset:512
	global_store_dwordx4 v[86:87], v[54:57], off offset:528
	v_cvt_pk_bf16_f32 v68, v54, v55
	v_cvt_pk_bf16_f32 v69, v56, v57
	v_pk_mul_f32 v[54:55], v[54:55], v[54:55]
	v_pk_mul_f32 v[56:57], v[56:57], v[56:57]
	v_cvt_pk_bf16_f32 v66, v62, v63
	v_cvt_pk_bf16_f32 v67, v64, v65
	v_pk_mul_f32 v[62:63], v[62:63], v[62:63]
	v_pk_mul_f32 v[64:65], v[64:65], v[64:65]
	v_add_f32_e32 v56, v56, v57
	v_add_f32_e32 v54, v54, v55
	v_add_f32_e32 v54, v54, v56
	v_add_f32_e32 v55, v64, v65
	v_add_f32_e32 v56, v62, v63
	v_add_f32_e32 v55, v56, v55
	v_add_f32_e32 v54, v55, v54
	v_add_f32_e32 v55, v80, v81
	v_add_f32_e32 v56, v78, v79
	v_add_f32_e32 v55, v56, v55
	v_add_f32_e32 v56, v76, v77
	v_add_f32_e32 v57, v74, v75
	v_add_f32_e32 v56, v57, v56
	v_add_f32_e32 v55, v56, v55
	v_add_f32_e32 v178, v55, v54
	v_lshlrev_b64 v[54:55], 11, v[84:85]
	global_store_dwordx4 v[88:89], v[66:69], off offset:256
	s_waitcnt vmcnt(7)
; __device__ __forceinline__ float sigmoidf_(float x) { return __builtin_amdgcn_rcpf(1.0f + __expf(-x)); }
; __device__ __forceinline__ float ssq4(const f32x4 o) { return (o[0] * o[0] + o[1] * o[1]) + (o[2] * o[2] + o[3] * o[3]); }
;     __device__ __forceinline__ void operator()(f32x4 (&acc)[2][2][4][2], const Unit& u, int wr, int wc, int fr, int fq) const {
;     ...
;             if (k < 3) {
; #pragma unroll
;                 for (int q = 0; q < 2; ++q)
; #pragma unroll
;                     for (int c = 0; c < 4; ++c) nxt[q][c] = *(const f32x4*)(h + (size_t)EPI_ROW(2 * k + 2 + q) * D + col0 + (c >> 1) * HALF + (c & 1) * 4);
;             }
; #pragma unroll
;             for (int q = 0; q < 2; ++q) { const int r = 2 * k + q, ai = r >> 2, m = r & 3; const size_t off = (size_t)EPI_ROW(r) * D + col0; float sr = 0.f;
;                 if (r < 7) {
; #pragma unroll
;                     for (int c = 0; c < 4; ++c) pnxt[c] = *(const u32x2*)(pp + (size_t)EPI_ROW(r + 1) * D + col0 + (c >> 1) * HALF + (c & 1) * 4);
;                 }
;                 asm volatile("" ::: "memory");
; #pragma unroll
;                 for (int bj = 0; bj < 2; ++bj) { f32x4 o2[2];
; #pragma unroll
;                     for (int n = 0; n < 2; ++n) { const f32x4 b = cur[q][2 * bj + n]; const u32x2 qw = pcur[2 * bj + n];
;                         const f32x4 pq = (f32x4){bflo(qw.x), bfhi(qw.x), bflo(qw.y), bfhi(qw.y)}; const f32x4 a = acc[ai][bj][m][n];
; #pragma unroll
;                         for (int j = 0; j < 4; ++j) o2[n][j] = b[j] + pq[j] * sigmoidf_(a[j]); }
;                     *(f32x4*)(h + off + bj * HALF) = o2[0]; *(f32x4*)(h + off + bj * HALF + 4) = o2[1];
;                     if (!LAST) { u32x4 w; w.x = cvt_pk_bf16(o2[0][0], o2[0][1]); w.y = cvt_pk_bf16(o2[0][2], o2[0][3]); w.z = cvt_pk_bf16(o2[1][0], o2[1][1]); w.w = cvt_pk_bf16(o2[1][2], o2[1][3]);
;                         *(u32x4*)(hb + off + bj * HALF) = w; sr += ssq4(o2[0]) + ssq4(o2[1]); } }
;                 s[ai][m] = sr;
;                 asm volatile("" ::: "memory");
; #pragma unroll
;                 for (int c = 0; c < 4; ++c) pcur[c] = pnxt[c];
;             }
	v_lshlrev_b32_e32 v56, 16, v58
	v_and_b32_e32 v57, 0xffff0000, v58
	v_lshl_add_u64 v[66:67], v[54:55], 0, v[152:153]
	v_lshlrev_b64 v[54:55], 12, v[242:243]
	v_lshl_add_u64 v[54:55], s[56:57], 0, v[54:55]
	v_lshl_add_u64 v[54:55], v[54:55], 0, v[198:199]
	global_load_dwordx4 v[86:89], v[54:55], off
	global_load_dwordx4 v[62:65], v[54:55], off offset:256
	v_mul_f32_e32 v54, 0xbfb8aa3b, v236
	v_mul_f32_e32 v55, 0xbfb8aa3b, v237
	v_exp_f32_e32 v54, v54
	v_exp_f32_e32 v55, v55
	v_add_u32_e32 v236, 0x80, v172
	v_add_f32_e32 v54, 1.0, v54
	v_add_f32_e32 v55, 1.0, v55
	v_rcp_f32_e32 v54, v54
	v_rcp_f32_e32 v55, v55
	v_lshlrev_b64 v[74:75], 11, v[242:243]
	v_ashrrev_i32_e32 v237, 31, v236
	v_lshl_add_u64 v[186:187], v[74:75], 0, v[152:153]
	v_pk_fma_f32 v[2:3], v[54:55], v[56:57], v[2:3]
	v_mul_f32_e32 v54, 0xbfb8aa3b, v234
	v_mul_f32_e32 v55, 0xbfb8aa3b, v235
	v_exp_f32_e32 v54, v54
	v_exp_f32_e32 v55, v55
	v_lshlrev_b32_e32 v56, 16, v59
	v_and_b32_e32 v57, 0xffff0000, v59
	v_add_f32_e32 v54, 1.0, v54
	v_add_f32_e32 v55, 1.0, v55
	v_rcp_f32_e32 v54, v54
	v_rcp_f32_e32 v55, v55
	v_lshl_add_u64 v[58:59], v[66:67], 1, s[54:55]
	v_lshlrev_b64 v[74:75], 12, v[228:229]
	v_lshl_add_u64 v[74:75], s[56:57], 0, v[74:75]
	v_pk_fma_f32 v[4:5], v[54:55], v[56:57], v[4:5]
	v_mul_f32_e32 v54, 0xbfb8aa3b, v232
	v_mul_f32_e32 v55, 0xbfb8aa3b, v233
	v_exp_f32_e32 v54, v54
	v_exp_f32_e32 v55, v55
	v_lshlrev_b32_e32 v56, 16, v60
	v_and_b32_e32 v57, 0xffff0000, v60
	v_add_f32_e32 v54, 1.0, v54
	v_add_f32_e32 v55, 1.0, v55
	v_rcp_f32_e32 v54, v54
	v_rcp_f32_e32 v55, v55
	v_add_u32_e32 v232, 0x90, v172
	v_ashrrev_i32_e32 v233, 31, v232
	v_lshl_add_u64 v[74:75], v[74:75], 0, v[198:199]
	v_pk_fma_f32 v[6:7], v[54:55], v[56:57], v[6:7]
	v_mul_f32_e32 v54, 0xbfb8aa3b, v222
	v_mul_f32_e32 v55, 0xbfb8aa3b, v223
	v_exp_f32_e32 v54, v54
	v_exp_f32_e32 v55, v55
	v_lshlrev_b32_e32 v56, 16, v61
	v_and_b32_e32 v57, 0xffff0000, v61
	v_add_f32_e32 v54, 1.0, v54
	v_add_f32_e32 v55, 1.0, v55
	v_rcp_f32_e32 v54, v54
	v_rcp_f32_e32 v55, v55
	v_add_f32_e32 v179, 1.0, v179
	v_rcp_f32_e32 v205, v179
	v_pk_fma_f32 v[8:9], v[54:55], v[56:57], v[8:9]
	v_cvt_pk_bf16_f32 v54, v2, v3
	v_cvt_pk_bf16_f32 v55, v4, v5
	v_cvt_pk_bf16_f32 v56, v6, v7
	v_cvt_pk_bf16_f32 v57, v8, v9
	global_store_dwordx4 v[82:83], v[2:5], off
	global_store_dwordx4 v[82:83], v[6:9], off offset:16
	global_store_dwordx4 v[58:59], v[54:57], off
	s_waitcnt vmcnt(4)
	v_lshlrev_b32_e32 v238, 16, v86
	v_mul_f32_e32 v54, 0xbfb8aa3b, v94
	v_mul_f32_e32 v55, 0xbfb8aa3b, v95
	v_exp_f32_e32 v54, v54
	v_exp_f32_e32 v55, v55
	v_lshlrev_b32_e32 v56, 16, v50
	v_and_b32_e32 v57, 0xffff0000, v50
	v_mul_f32_e32 v50, 0xbfb8aa3b, v96
	v_add_f32_e32 v54, 1.0, v54
	v_add_f32_e32 v55, 1.0, v55
	v_exp_f32_e32 v50, v50
	v_rcp_f32_e32 v54, v54
	v_rcp_f32_e32 v55, v55
	v_and_b32_e32 v239, 0xffff0000, v86
	v_add_f32_e32 v50, 1.0, v50
	v_mul_f32_e32 v86, 0xbfb8aa3b, v224
	v_pk_fma_f32 v[10:11], v[54:55], v[56:57], v[10:11]
	v_rcp_f32_e32 v54, v50
	v_mul_f32_e32 v50, 0xbfb8aa3b, v97
	v_exp_f32_e32 v50, v50
	v_exp_f32_e32 v86, v86
	v_pk_fma_f32 v[18:19], v[226:227], v[238:239], v[18:19]
	v_add_f32_e32 v50, 1.0, v50
	v_rcp_f32_e32 v55, v50
	v_lshlrev_b32_e32 v50, 16, v51
	v_and_b32_e32 v51, 0xffff0000, v51
	v_add_f32_e32 v86, 1.0, v86
	v_pk_fma_f32 v[12:13], v[54:55], v[50:51], v[12:13]
	v_mul_f32_e32 v50, 0xbfb8aa3b, v90
	v_mul_f32_e32 v51, 0xbfb8aa3b, v91
	v_exp_f32_e32 v50, v50
	v_exp_f32_e32 v51, v51
	v_lshlrev_b32_e32 v54, 16, v52
	v_and_b32_e32 v55, 0xffff0000, v52
	v_add_f32_e32 v50, 1.0, v50
	v_add_f32_e32 v51, 1.0, v51
	v_rcp_f32_e32 v50, v50
	v_rcp_f32_e32 v51, v51
	v_rcp_f32_e32 v224, v86
	v_mul_f32_e32 v86, 0xbfb8aa3b, v225
	v_exp_f32_e32 v86, v86
	v_pk_fma_f32 v[14:15], v[50:51], v[54:55], v[14:15]
	v_mul_f32_e32 v50, 0xbfb8aa3b, v92
	v_mul_f32_e32 v51, 0xbfb8aa3b, v93
	v_exp_f32_e32 v50, v50
	v_exp_f32_e32 v51, v51
	v_lshlrev_b32_e32 v52, 16, v53
	v_and_b32_e32 v53, 0xffff0000, v53
	v_add_f32_e32 v50, 1.0, v50
	v_add_f32_e32 v51, 1.0, v51
	v_rcp_f32_e32 v50, v50
	v_rcp_f32_e32 v51, v51
	v_add_f32_e32 v86, 1.0, v86
	v_rcp_f32_e32 v225, v86
	v_lshlrev_b32_e32 v86, 16, v87
	v_pk_fma_f32 v[16:17], v[50:51], v[52:53], v[16:17]
	v_cvt_pk_bf16_f32 v50, v10, v11
	v_cvt_pk_bf16_f32 v51, v12, v13
	v_cvt_pk_bf16_f32 v52, v14, v15
	v_cvt_pk_bf16_f32 v53, v16, v17
	global_store_dwordx4 v[82:83], v[10:13], off offset:512
	global_store_dwordx4 v[82:83], v[14:17], off offset:528
	global_store_dwordx4 v[58:59], v[50:53], off offset:256
	v_lshlrev_b64 v[58:59], 13, v[232:233]
	v_lshl_add_u64 v[222:223], v[118:119], 0, v[58:59]
	v_lshlrev_b64 v[50:51], 13, v[236:237]
	v_lshl_add_u64 v[234:235], v[118:119], 0, v[50:51]
	global_load_dwordx4 v[54:57], v[234:235], off offset:16
	global_load_dwordx4 v[50:53], v[234:235], off
	global_load_dwordx4 v[78:81], v[234:235], off offset:528
	global_load_dwordx4 v[66:69], v[234:235], off offset:512
	global_load_dwordx4 v[82:85], v[222:223], off offset:16
	global_load_dwordx4 v[90:93], v[222:223], off
	global_load_dwordx4 v[58:61], v[222:223], off offset:528
	global_load_dwordx4 v[70:73], v[222:223], off offset:512
	global_load_dwordx4 v[94:97], v[74:75], off
	s_nop 0
	global_load_dwordx4 v[74:77], v[74:75], off offset:256
	v_and_b32_e32 v87, 0xffff0000, v87
	v_pk_fma_f32 v[20:21], v[224:225], v[86:87], v[20:21]
	v_mul_f32_e32 v86, 0xbfb8aa3b, v128
	v_mul_f32_e32 v87, 0xbfb8aa3b, v129
	v_exp_f32_e32 v86, v86
	v_exp_f32_e32 v87, v87
	v_lshlrev_b32_e32 v128, 16, v88
	v_and_b32_e32 v129, 0xffff0000, v88
	v_add_f32_e32 v86, 1.0, v86
	v_add_f32_e32 v87, 1.0, v87
	v_rcp_f32_e32 v86, v86
	v_rcp_f32_e32 v87, v87
	v_lshlrev_b32_e32 v88, 16, v89
	v_and_b32_e32 v89, 0xffff0000, v89
	v_pk_fma_f32 v[22:23], v[86:87], v[128:129], v[22:23]
	v_mul_f32_e32 v86, 0xbfb8aa3b, v126
	v_mul_f32_e32 v87, 0xbfb8aa3b, v127
	v_exp_f32_e32 v86, v86
	v_exp_f32_e32 v87, v87
	v_lshl_add_u64 v[126:127], v[186:187], 1, s[54:55]
	v_add_u32_e32 v224, 0xb0, v172
	v_add_f32_e32 v86, 1.0, v86
	v_add_f32_e32 v87, 1.0, v87
	v_rcp_f32_e32 v86, v86
	v_rcp_f32_e32 v87, v87
	v_ashrrev_i32_e32 v225, 31, v224
	v_pk_fma_f32 v[24:25], v[86:87], v[88:89], v[24:25]
	v_cvt_pk_bf16_f32 v86, v18, v19
	v_cvt_pk_bf16_f32 v87, v20, v21
	v_cvt_pk_bf16_f32 v88, v22, v23
	v_cvt_pk_bf16_f32 v89, v24, v25
	global_store_dwordx4 v[230:231], v[18:21], off
	global_store_dwordx4 v[230:231], v[22:25], off offset:16
	global_store_dwordx4 v[126:127], v[86:89], off
	s_nop 1
	v_mul_f32_e32 v86, 0xbfb8aa3b, v124
	v_mul_f32_e32 v87, 0xbfb8aa3b, v125
	v_exp_f32_e32 v86, v86
	v_exp_f32_e32 v87, v87
	s_waitcnt vmcnt(19)
; __device__ __forceinline__ float sigmoidf_(float x) { return __builtin_amdgcn_rcpf(1.0f + __expf(-x)); }
; __device__ __forceinline__ float ssq4(const f32x4 o) { return (o[0] * o[0] + o[1] * o[1]) + (o[2] * o[2] + o[3] * o[3]); }
;     __device__ __forceinline__ void operator()(f32x4 (&acc)[2][2][4][2], const Unit& u, int wr, int wc, int fr, int fq) const {
;     ...
;             if (k < 3) {
; #pragma unroll
;                 for (int q = 0; q < 2; ++q)
; #pragma unroll
;                     for (int c = 0; c < 4; ++c) nxt[q][c] = *(const f32x4*)(h + (size_t)EPI_ROW(2 * k + 2 + q) * D + col0 + (c >> 1) * HALF + (c & 1) * 4);
;             }
; #pragma unroll
;             for (int q = 0; q < 2; ++q) { const int r = 2 * k + q, ai = r >> 2, m = r & 3; const size_t off = (size_t)EPI_ROW(r) * D + col0; float sr = 0.f;
;                 if (r < 7) {
; #pragma unroll
;                     for (int c = 0; c < 4; ++c) pnxt[c] = *(const u32x2*)(pp + (size_t)EPI_ROW(r + 1) * D + col0 + (c >> 1) * HALF + (c & 1) * 4);
;                 }
;                 asm volatile("" ::: "memory");
; #pragma unroll
;                 for (int bj = 0; bj < 2; ++bj) { f32x4 o2[2];
; #pragma unroll
;                     for (int n = 0; n < 2; ++n) { const f32x4 b = cur[q][2 * bj + n]; const u32x2 qw = pcur[2 * bj + n];
;                         const f32x4 pq = (f32x4){bflo(qw.x), bfhi(qw.x), bflo(qw.y), bfhi(qw.y)}; const f32x4 a = acc[ai][bj][m][n];
; #pragma unroll
;                         for (int j = 0; j < 4; ++j) o2[n][j] = b[j] + pq[j] * sigmoidf_(a[j]); }
;                     *(f32x4*)(h + off + bj * HALF) = o2[0]; *(f32x4*)(h + off + bj * HALF + 4) = o2[1];
;                     if (!LAST) { u32x4 w; w.x = cvt_pk_bf16(o2[0][0], o2[0][1]); w.y = cvt_pk_bf16(o2[0][2], o2[0][3]); w.z = cvt_pk_bf16(o2[1][0], o2[1][1]); w.w = cvt_pk_bf16(o2[1][2], o2[1][3]);
;                         *(u32x4*)(hb + off + bj * HALF) = w; sr += ssq4(o2[0]) + ssq4(o2[1]); } }
;                 s[ai][m] = sr;
;                 asm volatile("" ::: "memory");
; #pragma unroll
;                 for (int c = 0; c < 4; ++c) pcur[c] = pnxt[c];
;             }
	v_lshlrev_b32_e32 v88, 16, v62
	v_and_b32_e32 v89, 0xffff0000, v62
	v_mul_f32_e32 v62, 0xbfb8aa3b, v122
	v_add_f32_e32 v86, 1.0, v86
	v_add_f32_e32 v87, 1.0, v87
	v_exp_f32_e32 v62, v62
	v_rcp_f32_e32 v86, v86
	v_rcp_f32_e32 v87, v87
	v_add_f32_e32 v62, 1.0, v62
	v_pk_fma_f32 v[26:27], v[86:87], v[88:89], v[26:27]
	v_rcp_f32_e32 v86, v62
	v_mul_f32_e32 v62, 0xbfb8aa3b, v123
	v_exp_f32_e32 v62, v62
	s_nop 0
	v_add_f32_e32 v62, 1.0, v62
	v_rcp_f32_e32 v87, v62
	v_lshlrev_b32_e32 v62, 16, v63
	v_and_b32_e32 v63, 0xffff0000, v63
	v_pk_fma_f32 v[28:29], v[86:87], v[62:63], v[28:29]
	v_mul_f32_e32 v62, 0xbfb8aa3b, v116
	v_mul_f32_e32 v63, 0xbfb8aa3b, v117
	v_exp_f32_e32 v62, v62
	v_exp_f32_e32 v63, v63
	v_lshlrev_b32_e32 v86, 16, v64
	v_and_b32_e32 v87, 0xffff0000, v64
	v_add_f32_e32 v62, 1.0, v62
	v_add_f32_e32 v63, 1.0, v63
	v_rcp_f32_e32 v62, v62
	v_rcp_f32_e32 v63, v63
	v_lshlrev_b32_e32 v64, 16, v65
	v_and_b32_e32 v65, 0xffff0000, v65
	v_pk_fma_f32 v[30:31], v[62:63], v[86:87], v[30:31]
	v_mul_f32_e32 v62, 0xbfb8aa3b, v114
	v_mul_f32_e32 v63, 0xbfb8aa3b, v115
	v_exp_f32_e32 v62, v62
	v_exp_f32_e32 v63, v63
	v_add_f32_e32 v62, 1.0, v62
	v_add_f32_e32 v63, 1.0, v63
	v_rcp_f32_e32 v62, v62
	v_rcp_f32_e32 v63, v63
	s_nop 0
	v_pk_fma_f32 v[32:33], v[62:63], v[64:65], v[32:33]
	v_cvt_pk_bf16_f32 v62, v26, v27
	v_cvt_pk_bf16_f32 v63, v28, v29
	v_cvt_pk_bf16_f32 v64, v30, v31
	v_cvt_pk_bf16_f32 v65, v32, v33
	global_store_dwordx4 v[230:231], v[26:29], off offset:512
	global_store_dwordx4 v[230:231], v[30:33], off offset:528
	global_store_dwordx4 v[126:127], v[62:65], off offset:256
	s_nop 1
	v_lshlrev_b64 v[62:63], 11, v[228:229]
	v_lshl_add_u64 v[86:87], v[62:63], 0, v[152:153]
	v_lshlrev_b64 v[62:63], 12, v[236:237]
	v_lshl_add_u64 v[62:63], s[56:57], 0, v[62:63]
	v_lshl_add_u64 v[62:63], v[62:63], 0, v[198:199]
	global_load_dwordx4 v[122:125], v[62:63], off
	global_load_dwordx4 v[114:117], v[62:63], off offset:256
	v_mul_f32_e32 v62, 0xbfb8aa3b, v112
	v_mul_f32_e32 v63, 0xbfb8aa3b, v113
	v_exp_f32_e32 v62, v62
	v_exp_f32_e32 v63, v63
	s_waitcnt vmcnt(9)
	v_lshlrev_b32_e32 v64, 16, v94
	v_and_b32_e32 v65, 0xffff0000, v94
	v_add_f32_e32 v62, 1.0, v62
	v_add_f32_e32 v63, 1.0, v63
	v_rcp_f32_e32 v62, v62
	v_rcp_f32_e32 v63, v63
	v_lshl_add_u64 v[86:87], v[86:87], 1, s[54:55]
	v_add_u32_e32 v228, 0xa0, v172
	v_pk_fma_f32 v[34:35], v[62:63], v[64:65], v[34:35]
	v_mul_f32_e32 v62, 0xbfb8aa3b, v110
	v_mul_f32_e32 v63, 0xbfb8aa3b, v111
	v_exp_f32_e32 v62, v62
	v_exp_f32_e32 v63, v63
	v_lshlrev_b32_e32 v64, 16, v95
	v_and_b32_e32 v65, 0xffff0000, v95
	v_add_f32_e32 v62, 1.0, v62
	v_add_f32_e32 v63, 1.0, v63
	v_rcp_f32_e32 v62, v62
	v_rcp_f32_e32 v63, v63
	v_ashrrev_i32_e32 v229, 31, v228
	v_pk_fma_f32 v[36:37], v[62:63], v[64:65], v[36:37]
	v_mul_f32_e32 v62, 0xbfb8aa3b, v108
	v_mul_f32_e32 v63, 0xbfb8aa3b, v109
	v_exp_f32_e32 v62, v62
	v_exp_f32_e32 v63, v63
	v_lshlrev_b32_e32 v64, 16, v96
	v_and_b32_e32 v65, 0xffff0000, v96
	v_add_f32_e32 v62, 1.0, v62
	v_add_f32_e32 v63, 1.0, v63
	v_rcp_f32_e32 v62, v62
	v_rcp_f32_e32 v63, v63
	s_waitcnt vmcnt(1)
	v_lshlrev_b32_e32 v230, 16, v122
	v_pk_fma_f32 v[38:39], v[62:63], v[64:65], v[38:39]
	v_mul_f32_e32 v62, 0xbfb8aa3b, v106
	v_mul_f32_e32 v63, 0xbfb8aa3b, v107
	v_exp_f32_e32 v62, v62
	v_exp_f32_e32 v63, v63
	v_lshlrev_b32_e32 v64, 16, v97
	v_and_b32_e32 v65, 0xffff0000, v97
	v_add_f32_e32 v62, 1.0, v62
	v_add_f32_e32 v63, 1.0, v63
	v_rcp_f32_e32 v62, v62
	v_rcp_f32_e32 v63, v63
	v_and_b32_e32 v231, 0xffff0000, v122
	v_mul_f32_e32 v122, 0xbfb8aa3b, v218
	v_exp_f32_e32 v122, v122
	v_pk_fma_f32 v[40:41], v[62:63], v[64:65], v[40:41]
	v_cvt_pk_bf16_f32 v62, v34, v35
	v_cvt_pk_bf16_f32 v63, v36, v37
	v_cvt_pk_bf16_f32 v64, v38, v39
	v_cvt_pk_bf16_f32 v65, v40, v41
	global_store_dwordx4 v[120:121], v[34:37], off
	global_store_dwordx4 v[120:121], v[38:41], off offset:16
	global_store_dwordx4 v[86:87], v[62:65], off
	v_add_f32_e32 v122, 1.0, v122
	v_rcp_f32_e32 v218, v122
	v_mul_f32_e32 v62, 0xbfb8aa3b, v104
	v_mul_f32_e32 v63, 0xbfb8aa3b, v105
	v_exp_f32_e32 v62, v62
	v_exp_f32_e32 v63, v63
	v_lshlrev_b32_e32 v64, 16, v74
	v_and_b32_e32 v65, 0xffff0000, v74
	v_add_f32_e32 v62, 1.0, v62
	v_add_f32_e32 v63, 1.0, v63
	v_rcp_f32_e32 v62, v62
	v_rcp_f32_e32 v63, v63
	v_mul_f32_e32 v122, 0xbfb8aa3b, v219
	v_exp_f32_e32 v122, v122
	v_pk_fma_f32 v[50:51], v[220:221], v[230:231], v[50:51]
	v_pk_fma_f32 v[42:43], v[62:63], v[64:65], v[42:43]
	v_mul_f32_e32 v62, 0xbfb8aa3b, v102
	v_mul_f32_e32 v63, 0xbfb8aa3b, v103
	v_exp_f32_e32 v62, v62
	v_exp_f32_e32 v63, v63
	v_lshlrev_b32_e32 v64, 16, v75
	v_and_b32_e32 v65, 0xffff0000, v75
	v_add_f32_e32 v62, 1.0, v62
	v_add_f32_e32 v63, 1.0, v63
	v_rcp_f32_e32 v62, v62
	v_rcp_f32_e32 v63, v63
	v_add_f32_e32 v122, 1.0, v122
	v_rcp_f32_e32 v219, v122
	v_lshlrev_b32_e32 v122, 16, v123
	v_pk_fma_f32 v[44:45], v[62:63], v[64:65], v[44:45]
	v_mul_f32_e32 v62, 0xbfb8aa3b, v100
	v_mul_f32_e32 v63, 0xbfb8aa3b, v101
	v_exp_f32_e32 v62, v62
	v_exp_f32_e32 v63, v63
	v_lshlrev_b32_e32 v64, 16, v76
	v_and_b32_e32 v65, 0xffff0000, v76
	v_add_f32_e32 v62, 1.0, v62
	v_add_f32_e32 v63, 1.0, v63
	v_rcp_f32_e32 v62, v62
	v_rcp_f32_e32 v63, v63
	v_and_b32_e32 v123, 0xffff0000, v123
	v_pk_fma_f32 v[52:53], v[218:219], v[122:123], v[52:53]
	v_mul_f32_e32 v122, 0xbfb8aa3b, v216
	v_pk_fma_f32 v[46:47], v[62:63], v[64:65], v[46:47]
	v_mul_f32_e32 v62, 0xbfb8aa3b, v98
	v_mul_f32_e32 v63, 0xbfb8aa3b, v99
	v_exp_f32_e32 v62, v62
	v_exp_f32_e32 v63, v63
	v_lshlrev_b32_e32 v64, 16, v77
	v_and_b32_e32 v65, 0xffff0000, v77
	v_add_f32_e32 v62, 1.0, v62
	v_add_f32_e32 v63, 1.0, v63
	v_rcp_f32_e32 v62, v62
; __device__ __forceinline__ float sigmoidf_(float x) { return __builtin_amdgcn_rcpf(1.0f + __expf(-x)); }
; __device__ __forceinline__ float ssq4(const f32x4 o) { return (o[0] * o[0] + o[1] * o[1]) + (o[2] * o[2] + o[3] * o[3]); }
;     __device__ __forceinline__ void operator()(f32x4 (&acc)[2][2][4][2], const Unit& u, int wr, int wc, int fr, int fq) const {
;     ...
;             if (k < 3) {
; #pragma unroll
;                 for (int q = 0; q < 2; ++q)
; #pragma unroll
;                     for (int c = 0; c < 4; ++c) nxt[q][c] = *(const f32x4*)(h + (size_t)EPI_ROW(2 * k + 2 + q) * D + col0 + (c >> 1) * HALF + (c & 1) * 4);
;             }
; #pragma unroll
;             for (int q = 0; q < 2; ++q) { const int r = 2 * k + q, ai = r >> 2, m = r & 3; const size_t off = (size_t)EPI_ROW(r) * D + col0; float sr = 0.f;
;                 if (r < 7) {
; #pragma unroll
;                     for (int c = 0; c < 4; ++c) pnxt[c] = *(const u32x2*)(pp + (size_t)EPI_ROW(r + 1) * D + col0 + (c >> 1) * HALF + (c & 1) * 4);
;                 }
;                 asm volatile("" ::: "memory");
; #pragma unroll
;                 for (int bj = 0; bj < 2; ++bj) { f32x4 o2[2];
; #pragma unroll
;                     for (int n = 0; n < 2; ++n) { const f32x4 b = cur[q][2 * bj + n]; const u32x2 qw = pcur[2 * bj + n];
;                         const f32x4 pq = (f32x4){bflo(qw.x), bfhi(qw.x), bflo(qw.y), bfhi(qw.y)}; const f32x4 a = acc[ai][bj][m][n];
; #pragma unroll
;                         for (int j = 0; j < 4; ++j) o2[n][j] = b[j] + pq[j] * sigmoidf_(a[j]); }
;                     *(f32x4*)(h + off + bj * HALF) = o2[0]; *(f32x4*)(h + off + bj * HALF + 4) = o2[1];
;                     if (!LAST) { u32x4 w; w.x = cvt_pk_bf16(o2[0][0], o2[0][1]); w.y = cvt_pk_bf16(o2[0][2], o2[0][3]); w.z = cvt_pk_bf16(o2[1][0], o2[1][1]); w.w = cvt_pk_bf16(o2[1][2], o2[1][3]);
;                         *(u32x4*)(hb + off + bj * HALF) = w; sr += ssq4(o2[0]) + ssq4(o2[1]); } }
;                 s[ai][m] = sr;
;                 asm volatile("" ::: "memory");
; #pragma unroll
;                 for (int c = 0; c < 4; ++c) pcur[c] = pnxt[c];
;             }
	v_rcp_f32_e32 v63, v63
	v_mul_f32_e32 v123, 0xbfb8aa3b, v217
	v_exp_f32_e32 v122, v122
	v_exp_f32_e32 v123, v123
	v_pk_fma_f32 v[48:49], v[62:63], v[64:65], v[48:49]
	v_cvt_pk_bf16_f32 v62, v42, v43
	v_cvt_pk_bf16_f32 v63, v44, v45
	v_cvt_pk_bf16_f32 v64, v46, v47
	v_cvt_pk_bf16_f32 v65, v48, v49
	global_store_dwordx4 v[120:121], v[42:45], off offset:512
	global_store_dwordx4 v[120:121], v[46:49], off offset:528
	global_store_dwordx4 v[86:87], v[62:65], off offset:256
	v_add_f32_e32 v122, 1.0, v122
	v_add_f32_e32 v123, 1.0, v123
	v_lshlrev_b64 v[62:63], 13, v[228:229]
	v_lshl_add_u64 v[226:227], v[118:119], 0, v[62:63]
	v_lshlrev_b64 v[62:63], 13, v[224:225]
	v_lshl_add_u64 v[172:173], v[118:119], 0, v[62:63]
	v_lshlrev_b64 v[118:119], 11, v[236:237]
	v_lshl_add_u64 v[186:187], v[118:119], 0, v[152:153]
	v_lshlrev_b64 v[118:119], 12, v[232:233]
	v_lshl_add_u64 v[118:119], s[56:57], 0, v[118:119]
	v_lshl_add_u64 v[118:119], v[118:119], 0, v[198:199]
	global_load_dwordx4 v[110:113], v[226:227], off offset:16
	global_load_dwordx4 v[106:109], v[226:227], off
	global_load_dwordx4 v[98:101], v[226:227], off offset:528
	global_load_dwordx4 v[102:105], v[226:227], off offset:512
	global_load_dwordx4 v[86:89], v[172:173], off offset:16
	global_load_dwordx4 v[94:97], v[172:173], off
	global_load_dwordx4 v[62:65], v[172:173], off offset:528
	global_load_dwordx4 v[74:77], v[172:173], off offset:512
	global_load_dwordx4 v[126:129], v[118:119], off
	s_nop 0
	global_load_dwordx4 v[118:121], v[118:119], off offset:256
	v_rcp_f32_e32 v122, v122
	v_rcp_f32_e32 v123, v123
	v_lshlrev_b32_e32 v216, 16, v124
	v_and_b32_e32 v217, 0xffff0000, v124
	v_lshlrev_b32_e32 v124, 16, v125
	v_pk_fma_f32 v[54:55], v[122:123], v[216:217], v[54:55]
	v_mul_f32_e32 v122, 0xbfb8aa3b, v214
	v_mul_f32_e32 v123, 0xbfb8aa3b, v215
	v_exp_f32_e32 v122, v122
	v_exp_f32_e32 v123, v123
	v_and_b32_e32 v125, 0xffff0000, v125
	v_lshl_add_u64 v[186:187], v[186:187], 1, s[54:55]
	v_add_f32_e32 v122, 1.0, v122
	v_add_f32_e32 v123, 1.0, v123
	v_rcp_f32_e32 v122, v122
	v_rcp_f32_e32 v123, v123
	s_nop 0
	v_pk_fma_f32 v[56:57], v[122:123], v[124:125], v[56:57]
	v_cvt_pk_bf16_f32 v122, v50, v51
	v_cvt_pk_bf16_f32 v123, v52, v53
	v_cvt_pk_bf16_f32 v124, v54, v55
	v_cvt_pk_bf16_f32 v125, v56, v57
	global_store_dwordx4 v[234:235], v[50:53], off
	global_store_dwordx4 v[234:235], v[54:57], off offset:16
	global_store_dwordx4 v[186:187], v[122:125], off
	s_nop 1
	v_mul_f32_e32 v122, 0xbfb8aa3b, v212
	v_mul_f32_e32 v123, 0xbfb8aa3b, v213
	v_exp_f32_e32 v122, v122
	v_exp_f32_e32 v123, v123
	s_waitcnt vmcnt(19)
	v_lshlrev_b32_e32 v124, 16, v114
	v_and_b32_e32 v125, 0xffff0000, v114
	v_mul_f32_e32 v114, 0xbfb8aa3b, v210
	v_add_f32_e32 v122, 1.0, v122
	v_add_f32_e32 v123, 1.0, v123
	v_exp_f32_e32 v114, v114
	v_rcp_f32_e32 v122, v122
	v_rcp_f32_e32 v123, v123
	v_add_f32_e32 v114, 1.0, v114
	v_pk_fma_f32 v[66:67], v[122:123], v[124:125], v[66:67]
	v_rcp_f32_e32 v122, v114
	v_mul_f32_e32 v114, 0xbfb8aa3b, v211
	v_exp_f32_e32 v114, v114
	s_nop 0
	v_add_f32_e32 v114, 1.0, v114
	v_rcp_f32_e32 v123, v114
	v_lshlrev_b32_e32 v114, 16, v115
	v_and_b32_e32 v115, 0xffff0000, v115
	v_pk_fma_f32 v[68:69], v[122:123], v[114:115], v[68:69]
	v_mul_f32_e32 v114, 0xbfb8aa3b, v208
	v_mul_f32_e32 v115, 0xbfb8aa3b, v209
	v_exp_f32_e32 v114, v114
	v_exp_f32_e32 v115, v115
	v_lshlrev_b32_e32 v122, 16, v116
	v_and_b32_e32 v123, 0xffff0000, v116
	v_add_f32_e32 v114, 1.0, v114
	v_add_f32_e32 v115, 1.0, v115
	v_rcp_f32_e32 v114, v114
	v_rcp_f32_e32 v115, v115
	v_lshlrev_b32_e32 v116, 16, v117
	v_and_b32_e32 v117, 0xffff0000, v117
	v_pk_fma_f32 v[78:79], v[114:115], v[122:123], v[78:79]
	v_mul_f32_e32 v114, 0xbfb8aa3b, v206
	v_mul_f32_e32 v115, 0xbfb8aa3b, v207
	v_exp_f32_e32 v114, v114
	v_exp_f32_e32 v115, v115
	v_add_f32_e32 v114, 1.0, v114
	v_add_f32_e32 v115, 1.0, v115
	v_rcp_f32_e32 v114, v114
	v_rcp_f32_e32 v115, v115
	s_waitcnt vmcnt(4)
	v_lshlrev_b32_e32 v206, 16, v126
	v_and_b32_e32 v207, 0xffff0000, v126
	v_mul_f32_e32 v126, 0xbfb8aa3b, v202
	v_pk_fma_f32 v[80:81], v[114:115], v[116:117], v[80:81]
	v_cvt_pk_bf16_f32 v114, v66, v67
	v_cvt_pk_bf16_f32 v115, v68, v69
	v_cvt_pk_bf16_f32 v116, v78, v79
	v_cvt_pk_bf16_f32 v117, v80, v81
	global_store_dwordx4 v[234:235], v[66:69], off offset:512
	global_store_dwordx4 v[234:235], v[78:81], off offset:528
	global_store_dwordx4 v[186:187], v[114:117], off offset:256
	v_exp_f32_e32 v126, v126
	v_pk_fma_f32 v[90:91], v[204:205], v[206:207], v[90:91]
	v_lshlrev_b64 v[114:115], 11, v[232:233]
	v_lshl_add_u64 v[186:187], v[114:115], 0, v[152:153]
	v_lshlrev_b64 v[114:115], 12, v[228:229]
	v_lshl_add_u64 v[114:115], s[56:57], 0, v[114:115]
	v_lshl_add_u64 v[114:115], v[114:115], 0, v[198:199]
	global_load_dwordx4 v[122:125], v[114:115], off
	s_nop 0
	global_load_dwordx4 v[114:117], v[114:115], off offset:256
	v_add_f32_e32 v126, 1.0, v126
	v_rcp_f32_e32 v202, v126
	v_mul_f32_e32 v126, 0xbfb8aa3b, v203
	v_exp_f32_e32 v126, v126
	v_lshl_add_u64 v[186:187], v[186:187], 1, s[54:55]
	v_add_f32_e32 v126, 1.0, v126
	v_rcp_f32_e32 v203, v126
	v_lshlrev_b32_e32 v126, 16, v127
	v_and_b32_e32 v127, 0xffff0000, v127
	v_pk_fma_f32 v[92:93], v[202:203], v[126:127], v[92:93]
	v_mul_f32_e32 v126, 0xbfb8aa3b, v200
	v_mul_f32_e32 v127, 0xbfb8aa3b, v201
	v_exp_f32_e32 v126, v126
	v_exp_f32_e32 v127, v127
	v_lshlrev_b32_e32 v200, 16, v128
	v_and_b32_e32 v201, 0xffff0000, v128
	v_add_f32_e32 v126, 1.0, v126
	v_add_f32_e32 v127, 1.0, v127
	v_rcp_f32_e32 v126, v126
	v_rcp_f32_e32 v127, v127
	v_lshlrev_b32_e32 v128, 16, v129
	v_and_b32_e32 v129, 0xffff0000, v129
	v_pk_fma_f32 v[82:83], v[126:127], v[200:201], v[82:83]
	v_mul_f32_e32 v126, 0xbfb8aa3b, v196
	v_mul_f32_e32 v127, 0xbfb8aa3b, v197
	v_exp_f32_e32 v126, v126
	v_exp_f32_e32 v127, v127
	v_add_f32_e32 v126, 1.0, v126
	v_add_f32_e32 v127, 1.0, v127
	v_rcp_f32_e32 v126, v126
	v_rcp_f32_e32 v127, v127
	s_nop 0
	v_pk_fma_f32 v[84:85], v[126:127], v[128:129], v[84:85]
	v_cvt_pk_bf16_f32 v126, v90, v91
	v_cvt_pk_bf16_f32 v127, v92, v93
	v_cvt_pk_bf16_f32 v128, v82, v83
	v_cvt_pk_bf16_f32 v129, v84, v85
	global_store_dwordx4 v[222:223], v[90:93], off
	global_store_dwordx4 v[222:223], v[82:85], off offset:16
	global_store_dwordx4 v[186:187], v[126:129], off
	s_nop 1
	v_mul_f32_e32 v126, 0xbfb8aa3b, v194
	v_mul_f32_e32 v127, 0xbfb8aa3b, v195
	v_exp_f32_e32 v126, v126
	v_exp_f32_e32 v127, v127
	s_waitcnt vmcnt(11)
; __device__ __forceinline__ float sigmoidf_(float x) { return __builtin_amdgcn_rcpf(1.0f + __expf(-x)); }
; __device__ __forceinline__ float ssq4(const f32x4 o) { return (o[0] * o[0] + o[1] * o[1]) + (o[2] * o[2] + o[3] * o[3]); }
;     __device__ __forceinline__ void operator()(f32x4 (&acc)[2][2][4][2], const Unit& u, int wr, int wc, int fr, int fq) const {
;     ...
;             if (k < 3) {
; #pragma unroll
;                 for (int q = 0; q < 2; ++q)
; #pragma unroll
;                     for (int c = 0; c < 4; ++c) nxt[q][c] = *(const f32x4*)(h + (size_t)EPI_ROW(2 * k + 2 + q) * D + col0 + (c >> 1) * HALF + (c & 1) * 4);
;             }
; #pragma unroll
;             for (int q = 0; q < 2; ++q) { const int r = 2 * k + q, ai = r >> 2, m = r & 3; const size_t off = (size_t)EPI_ROW(r) * D + col0; float sr = 0.f;
;                 if (r < 7) {
; #pragma unroll
;                     for (int c = 0; c < 4; ++c) pnxt[c] = *(const u32x2*)(pp + (size_t)EPI_ROW(r + 1) * D + col0 + (c >> 1) * HALF + (c & 1) * 4);
;                 }
;                 asm volatile("" ::: "memory");
; #pragma unroll
;                 for (int bj = 0; bj < 2; ++bj) { f32x4 o2[2];
; #pragma unroll
;                     for (int n = 0; n < 2; ++n) { const f32x4 b = cur[q][2 * bj + n]; const u32x2 qw = pcur[2 * bj + n];
;                         const f32x4 pq = (f32x4){bflo(qw.x), bfhi(qw.x), bflo(qw.y), bfhi(qw.y)}; const f32x4 a = acc[ai][bj][m][n];
; #pragma unroll
;                         for (int j = 0; j < 4; ++j) o2[n][j] = b[j] + pq[j] * sigmoidf_(a[j]); }
;                     *(f32x4*)(h + off + bj * HALF) = o2[0]; *(f32x4*)(h + off + bj * HALF + 4) = o2[1];
;                     if (!LAST) { u32x4 w; w.x = cvt_pk_bf16(o2[0][0], o2[0][1]); w.y = cvt_pk_bf16(o2[0][2], o2[0][3]); w.z = cvt_pk_bf16(o2[1][0], o2[1][1]); w.w = cvt_pk_bf16(o2[1][2], o2[1][3]);
;                         *(u32x4*)(hb + off + bj * HALF) = w; sr += ssq4(o2[0]) + ssq4(o2[1]); } }
;                 s[ai][m] = sr;
;                 asm volatile("" ::: "memory");
; #pragma unroll
;                 for (int c = 0; c < 4; ++c) pcur[c] = pnxt[c];
;             }
	v_lshlrev_b32_e32 v128, 16, v118
	v_and_b32_e32 v129, 0xffff0000, v118
	v_mul_f32_e32 v118, 0xbfb8aa3b, v192
	v_add_f32_e32 v126, 1.0, v126
	v_add_f32_e32 v127, 1.0, v127
	v_exp_f32_e32 v118, v118
	v_rcp_f32_e32 v126, v126
	v_rcp_f32_e32 v127, v127
	v_add_f32_e32 v118, 1.0, v118
	v_pk_fma_f32 v[70:71], v[126:127], v[128:129], v[70:71]
	v_rcp_f32_e32 v126, v118
	v_mul_f32_e32 v118, 0xbfb8aa3b, v193
	v_exp_f32_e32 v118, v118
	s_nop 0
	v_add_f32_e32 v118, 1.0, v118
	v_rcp_f32_e32 v127, v118
	v_lshlrev_b32_e32 v118, 16, v119
	v_and_b32_e32 v119, 0xffff0000, v119
	v_pk_fma_f32 v[72:73], v[126:127], v[118:119], v[72:73]
	v_mul_f32_e32 v118, 0xbfb8aa3b, v190
	v_mul_f32_e32 v119, 0xbfb8aa3b, v191
	v_exp_f32_e32 v118, v118
	v_exp_f32_e32 v119, v119
	v_lshlrev_b32_e32 v126, 16, v120
	v_and_b32_e32 v127, 0xffff0000, v120
	v_add_f32_e32 v118, 1.0, v118
	v_add_f32_e32 v119, 1.0, v119
	v_rcp_f32_e32 v118, v118
	v_rcp_f32_e32 v119, v119
	v_lshlrev_b32_e32 v120, 16, v121
	v_and_b32_e32 v121, 0xffff0000, v121
	v_pk_fma_f32 v[58:59], v[118:119], v[126:127], v[58:59]
	v_mul_f32_e32 v118, 0xbfb8aa3b, v188
	v_mul_f32_e32 v119, 0xbfb8aa3b, v189
	v_exp_f32_e32 v118, v118
	v_exp_f32_e32 v119, v119
	s_waitcnt vmcnt(4)
	v_lshlrev_b32_e32 v188, 16, v122
	v_and_b32_e32 v189, 0xffff0000, v122
	v_add_f32_e32 v118, 1.0, v118
	v_add_f32_e32 v119, 1.0, v119
	v_mul_f32_e32 v122, 0xbfb8aa3b, v174
	v_rcp_f32_e32 v118, v118
	v_rcp_f32_e32 v119, v119
	v_exp_f32_e32 v122, v122
	v_pk_fma_f32 v[106:107], v[176:177], v[188:189], v[106:107]
	v_pk_fma_f32 v[60:61], v[118:119], v[120:121], v[60:61]
	v_add_f32_e32 v122, 1.0, v122
	v_cvt_pk_bf16_f32 v118, v70, v71
	v_cvt_pk_bf16_f32 v119, v72, v73
	v_cvt_pk_bf16_f32 v120, v58, v59
	v_cvt_pk_bf16_f32 v121, v60, v61
	v_rcp_f32_e32 v174, v122
	v_mul_f32_e32 v122, 0xbfb8aa3b, v175
	global_store_dwordx4 v[222:223], v[70:73], off offset:512
	global_store_dwordx4 v[222:223], v[58:61], off offset:528
	global_store_dwordx4 v[186:187], v[118:121], off offset:256
	v_exp_f32_e32 v122, v122
	s_nop 0
	v_lshlrev_b64 v[118:119], 11, v[228:229]
	v_lshl_add_u64 v[186:187], v[118:119], 0, v[152:153]
	v_lshlrev_b64 v[118:119], 12, v[224:225]
	v_lshl_add_u64 v[118:119], s[56:57], 0, v[118:119]
	v_lshl_add_u64 v[118:119], v[118:119], 0, v[198:199]
	global_load_dwordx4 v[126:129], v[118:119], off
	s_nop 0
	global_load_dwordx4 v[118:121], v[118:119], off offset:256
	v_add_f32_e32 v122, 1.0, v122
	v_rcp_f32_e32 v175, v122
	v_lshlrev_b32_e32 v122, 16, v123
	v_and_b32_e32 v123, 0xffff0000, v123
	v_pk_fma_f32 v[108:109], v[174:175], v[122:123], v[108:109]
	v_mul_f32_e32 v122, 0xbfb8aa3b, v170
	v_mul_f32_e32 v123, 0xbfb8aa3b, v171
	v_exp_f32_e32 v122, v122
	v_exp_f32_e32 v123, v123
	v_lshlrev_b32_e32 v170, 16, v124
	v_and_b32_e32 v171, 0xffff0000, v124
	v_add_f32_e32 v122, 1.0, v122
	v_add_f32_e32 v123, 1.0, v123
	v_rcp_f32_e32 v122, v122
	v_rcp_f32_e32 v123, v123
	v_lshlrev_b32_e32 v124, 16, v125
	v_and_b32_e32 v125, 0xffff0000, v125
	v_pk_fma_f32 v[110:111], v[122:123], v[170:171], v[110:111]
	v_mul_f32_e32 v122, 0xbfb8aa3b, v168
	v_mul_f32_e32 v123, 0xbfb8aa3b, v169
	v_exp_f32_e32 v122, v122
	v_exp_f32_e32 v123, v123
	v_lshl_add_u64 v[168:169], v[186:187], 1, s[54:55]
	v_add_f32_e32 v122, 1.0, v122
	v_add_f32_e32 v123, 1.0, v123
	v_rcp_f32_e32 v122, v122
	v_rcp_f32_e32 v123, v123
	s_nop 0
	v_pk_fma_f32 v[112:113], v[122:123], v[124:125], v[112:113]
	v_cvt_pk_bf16_f32 v122, v106, v107
	v_cvt_pk_bf16_f32 v123, v108, v109
	v_cvt_pk_bf16_f32 v124, v110, v111
	v_cvt_pk_bf16_f32 v125, v112, v113
	global_store_dwordx4 v[226:227], v[106:109], off
	global_store_dwordx4 v[226:227], v[110:113], off offset:16
	global_store_dwordx4 v[168:169], v[122:125], off
	s_nop 1
	v_mul_f32_e32 v122, 0xbfb8aa3b, v166
	v_mul_f32_e32 v123, 0xbfb8aa3b, v167
	v_exp_f32_e32 v122, v122
	v_exp_f32_e32 v123, v123
	s_waitcnt vmcnt(11)
	v_lshlrev_b32_e32 v124, 16, v114
	v_and_b32_e32 v125, 0xffff0000, v114
	v_mul_f32_e32 v114, 0xbfb8aa3b, v150
	v_add_f32_e32 v122, 1.0, v122
	v_add_f32_e32 v123, 1.0, v123
	v_exp_f32_e32 v114, v114
	v_rcp_f32_e32 v122, v122
	v_rcp_f32_e32 v123, v123
	v_add_f32_e32 v114, 1.0, v114
	v_pk_fma_f32 v[102:103], v[122:123], v[124:125], v[102:103]
	v_rcp_f32_e32 v122, v114
	v_mul_f32_e32 v114, 0xbfb8aa3b, v151
	v_exp_f32_e32 v114, v114
	s_nop 0
	v_add_f32_e32 v114, 1.0, v114
	v_rcp_f32_e32 v123, v114
	v_lshlrev_b32_e32 v114, 16, v115
	v_and_b32_e32 v115, 0xffff0000, v115
	v_pk_fma_f32 v[104:105], v[122:123], v[114:115], v[104:105]
	v_mul_f32_e32 v114, 0xbfb8aa3b, v148
	v_mul_f32_e32 v115, 0xbfb8aa3b, v149
	v_exp_f32_e32 v114, v114
	v_exp_f32_e32 v115, v115
	v_lshlrev_b32_e32 v122, 16, v116
	v_and_b32_e32 v123, 0xffff0000, v116
	v_add_f32_e32 v114, 1.0, v114
	v_add_f32_e32 v115, 1.0, v115
	v_rcp_f32_e32 v114, v114
	v_rcp_f32_e32 v115, v115
	v_lshlrev_b32_e32 v116, 16, v117
	v_and_b32_e32 v117, 0xffff0000, v117
	v_pk_fma_f32 v[98:99], v[114:115], v[122:123], v[98:99]
	v_mul_f32_e32 v114, 0xbfb8aa3b, v146
	v_mul_f32_e32 v115, 0xbfb8aa3b, v147
	v_exp_f32_e32 v114, v114
	v_exp_f32_e32 v115, v115
	v_add_f32_e32 v114, 1.0, v114
	v_add_f32_e32 v115, 1.0, v115
	v_rcp_f32_e32 v114, v114
	v_rcp_f32_e32 v115, v115
	s_nop 0
	v_pk_fma_f32 v[100:101], v[114:115], v[116:117], v[100:101]
	v_cvt_pk_bf16_f32 v114, v102, v103
	v_cvt_pk_bf16_f32 v115, v104, v105
	v_cvt_pk_bf16_f32 v116, v98, v99
	v_cvt_pk_bf16_f32 v117, v100, v101
	global_store_dwordx4 v[226:227], v[102:105], off offset:512
	global_store_dwordx4 v[226:227], v[98:101], off offset:528
	global_store_dwordx4 v[168:169], v[114:117], off offset:256
	s_nop 1
	v_lshlrev_b64 v[114:115], 11, v[224:225]
	v_lshl_add_u64 v[122:123], v[114:115], 0, v[152:153]
	v_mul_f32_e32 v114, 0xbfb8aa3b, v144
	v_mul_f32_e32 v115, 0xbfb8aa3b, v145
	v_exp_f32_e32 v114, v114
	v_exp_f32_e32 v115, v115
	s_waitcnt vmcnt(7)
; __device__ __forceinline__ float sigmoidf_(float x) { return __builtin_amdgcn_rcpf(1.0f + __expf(-x)); }
; __device__ __forceinline__ float shx(float v, int o, int lane) { return __builtin_bit_cast(float, __builtin_amdgcn_ds_bpermute((lane ^ o) << 2, __builtin_bit_cast(int, v))); }
; __device__ __forceinline__ float ssq4(const f32x4 o) { return (o[0] * o[0] + o[1] * o[1]) + (o[2] * o[2] + o[3] * o[3]); }
; template <bool SIXTEEN> __device__ __forceinline__ void tile_ssq(const float (&s)[2][4], const Unit& u, int wr, int wc, int fr, int fq, float* ssq, LAS float* ptab) {
;     ...
;         for (int m = 0; m < 4; ++m) { float v = s[ai][m]; v += shx(v, 16, lane); v += shx(v, 32, lane); if (fq == 0) ptab[(ai * HALF + wr * 64 + m * 16 + fr) * 4 + wc] = v; }
;     __device__ __forceinline__ void operator()(f32x4 (&acc)[2][2][4][2], const Unit& u, int wr, int wc, int fr, int fq) const {
;     ...
;             for (int q = 0; q < 2; ++q) { const int r = 2 * k + q, ai = r >> 2, m = r & 3; const size_t off = (size_t)EPI_ROW(r) * D + col0; float sr = 0.f;
;                 if (r < 7) {
; #pragma unroll
;                     for (int c = 0; c < 4; ++c) pnxt[c] = *(const u32x2*)(pp + (size_t)EPI_ROW(r + 1) * D + col0 + (c >> 1) * HALF + (c & 1) * 4);
;                 }
;                 asm volatile("" ::: "memory");
; #pragma unroll
;                 for (int bj = 0; bj < 2; ++bj) { f32x4 o2[2];
; #pragma unroll
;                     for (int n = 0; n < 2; ++n) { const f32x4 b = cur[q][2 * bj + n]; const u32x2 qw = pcur[2 * bj + n];
;                         const f32x4 pq = (f32x4){bflo(qw.x), bfhi(qw.x), bflo(qw.y), bfhi(qw.y)}; const f32x4 a = acc[ai][bj][m][n];
; #pragma unroll
;                         for (int j = 0; j < 4; ++j) o2[n][j] = b[j] + pq[j] * sigmoidf_(a[j]); }
;                     *(f32x4*)(h + off + bj * HALF) = o2[0]; *(f32x4*)(h + off + bj * HALF + 4) = o2[1];
;                     if (!LAST) { u32x4 w; w.x = cvt_pk_bf16(o2[0][0], o2[0][1]); w.y = cvt_pk_bf16(o2[0][2], o2[0][3]); w.z = cvt_pk_bf16(o2[1][0], o2[1][1]); w.w = cvt_pk_bf16(o2[1][2], o2[1][3]);
;                         *(u32x4*)(hb + off + bj * HALF) = w; sr += ssq4(o2[0]) + ssq4(o2[1]); } }
;                 s[ai][m] = sr;
;                 asm volatile("" ::: "memory");
; #pragma unroll
;                 for (int c = 0; c < 4; ++c) pcur[c] = pnxt[c];
;             }
	v_lshlrev_b32_e32 v116, 16, v126
	v_and_b32_e32 v117, 0xffff0000, v126
	v_add_f32_e32 v114, 1.0, v114
	v_add_f32_e32 v115, 1.0, v115
	v_rcp_f32_e32 v114, v114
	v_rcp_f32_e32 v115, v115
	v_lshl_add_u64 v[122:123], v[122:123], 1, s[54:55]
	v_pk_fma_f32 v[94:95], v[114:115], v[116:117], v[94:95]
	v_mul_f32_e32 v114, 0xbfb8aa3b, v142
	v_mul_f32_e32 v115, 0xbfb8aa3b, v143
	v_exp_f32_e32 v114, v114
	v_exp_f32_e32 v115, v115
	v_lshlrev_b32_e32 v116, 16, v127
	v_and_b32_e32 v117, 0xffff0000, v127
	v_add_f32_e32 v114, 1.0, v114
	v_add_f32_e32 v115, 1.0, v115
	v_rcp_f32_e32 v114, v114
	v_rcp_f32_e32 v115, v115
	s_nop 0
	v_pk_fma_f32 v[96:97], v[114:115], v[116:117], v[96:97]
	v_mul_f32_e32 v114, 0xbfb8aa3b, v140
	v_mul_f32_e32 v115, 0xbfb8aa3b, v141
	v_exp_f32_e32 v114, v114
	v_exp_f32_e32 v115, v115
	v_lshlrev_b32_e32 v116, 16, v128
	v_and_b32_e32 v117, 0xffff0000, v128
	v_add_f32_e32 v114, 1.0, v114
	v_add_f32_e32 v115, 1.0, v115
	v_rcp_f32_e32 v114, v114
	v_rcp_f32_e32 v115, v115
	s_nop 0
	v_pk_fma_f32 v[86:87], v[114:115], v[116:117], v[86:87]
	v_mul_f32_e32 v114, 0xbfb8aa3b, v138
	v_mul_f32_e32 v115, 0xbfb8aa3b, v139
	v_exp_f32_e32 v114, v114
	v_exp_f32_e32 v115, v115
	v_lshlrev_b32_e32 v116, 16, v129
	v_and_b32_e32 v117, 0xffff0000, v129
	v_add_f32_e32 v114, 1.0, v114
	v_add_f32_e32 v115, 1.0, v115
	v_rcp_f32_e32 v114, v114
	v_rcp_f32_e32 v115, v115
	s_nop 0
	v_pk_fma_f32 v[88:89], v[114:115], v[116:117], v[88:89]
	v_cvt_pk_bf16_f32 v114, v94, v95
	v_cvt_pk_bf16_f32 v115, v96, v97
	v_cvt_pk_bf16_f32 v116, v86, v87
	v_cvt_pk_bf16_f32 v117, v88, v89
	global_store_dwordx4 v[172:173], v[94:97], off
	global_store_dwordx4 v[172:173], v[86:89], off offset:16
	global_store_dwordx4 v[122:123], v[114:117], off
	s_nop 1
	v_mul_f32_e32 v114, 0xbfb8aa3b, v136
	v_mul_f32_e32 v115, 0xbfb8aa3b, v137
	v_exp_f32_e32 v114, v114
	v_exp_f32_e32 v115, v115
	s_waitcnt vmcnt(9)
	v_lshlrev_b32_e32 v116, 16, v118
	v_and_b32_e32 v117, 0xffff0000, v118
	v_add_f32_e32 v114, 1.0, v114
	v_add_f32_e32 v115, 1.0, v115
	v_rcp_f32_e32 v114, v114
	v_rcp_f32_e32 v115, v115
	s_nop 0
	v_pk_fma_f32 v[74:75], v[114:115], v[116:117], v[74:75]
	v_mul_f32_e32 v114, 0xbfb8aa3b, v134
	v_mul_f32_e32 v115, 0xbfb8aa3b, v135
	v_exp_f32_e32 v114, v114
	v_exp_f32_e32 v115, v115
	v_lshlrev_b32_e32 v116, 16, v119
	v_and_b32_e32 v117, 0xffff0000, v119
	v_add_f32_e32 v114, 1.0, v114
	v_add_f32_e32 v115, 1.0, v115
	v_rcp_f32_e32 v114, v114
	v_rcp_f32_e32 v115, v115
	s_nop 0
	v_pk_fma_f32 v[76:77], v[114:115], v[116:117], v[76:77]
	v_mul_f32_e32 v114, 0xbfb8aa3b, v132
	v_mul_f32_e32 v115, 0xbfb8aa3b, v133
	v_exp_f32_e32 v114, v114
	v_exp_f32_e32 v115, v115
	v_lshlrev_b32_e32 v116, 16, v120
	v_and_b32_e32 v117, 0xffff0000, v120
	v_add_f32_e32 v114, 1.0, v114
	v_add_f32_e32 v115, 1.0, v115
	v_rcp_f32_e32 v114, v114
	v_rcp_f32_e32 v115, v115
	s_nop 0
	v_pk_fma_f32 v[62:63], v[114:115], v[116:117], v[62:63]
	v_mul_f32_e32 v114, 0xbfb8aa3b, v130
	v_mul_f32_e32 v115, 0xbfb8aa3b, v131
	v_exp_f32_e32 v114, v114
	v_exp_f32_e32 v115, v115
	v_lshlrev_b32_e32 v116, 16, v121
	v_and_b32_e32 v117, 0xffff0000, v121
	v_add_f32_e32 v114, 1.0, v114
	v_add_f32_e32 v115, 1.0, v115
	v_rcp_f32_e32 v114, v114
	v_rcp_f32_e32 v115, v115
	s_nop 0
	v_pk_fma_f32 v[64:65], v[114:115], v[116:117], v[64:65]
	v_cvt_pk_bf16_f32 v114, v74, v75
	v_cvt_pk_bf16_f32 v115, v76, v77
	v_cvt_pk_bf16_f32 v116, v62, v63
	v_cvt_pk_bf16_f32 v117, v64, v65
	global_store_dwordx4 v[172:173], v[74:77], off offset:512
	global_store_dwordx4 v[172:173], v[62:65], off offset:528
	global_store_dwordx4 v[122:123], v[114:117], off offset:256
	s_nop 1
	v_and_b32_e32 v114, 63, v183
	v_lshlrev_b32_e32 v115, 2, v114
	v_xor_b32_e32 v116, 64, v115
	ds_bpermute_b32 v117, v116, v178
	v_xor_b32_e32 v115, 0x80, v115
	s_waitcnt lgkmcnt(0)
	v_add_f32_e32 v118, v178, v117
	ds_bpermute_b32 v119, v115, v118
	v_lshl_add_u32 v117, v184, 4, s4
	s_and_saveexec_b64 s[8:9], vcc
	s_cbranch_execz .LBB0_2337
	s_waitcnt lgkmcnt(0)
	v_add_f32_e32 v118, v118, v119
	ds_write_b32 v117, v118
